# adds hand-written 5-stage ring K-loops for the two K=2816 GEMM phases (7,16) on top of six GEMM ring loops, pipelined conv d-loop, hyena post/pre fast paths
# speedup vs baseline: 1.0570x; 1.0131x over previous
; DI int tid512() { int t = threadIdx_x_raw(); asm volatile("" : "+v"(t)); return t; }
; #define G_LOADA(kt_) { _Pragma("unroll") for (int i = 0; i < 4; ++i) ra[i] = al(lrow + 64 * i, (kt_) * 64 + lck * 8); }
; #define G_LOADB(kt_) { _Pragma("unroll") for (int i = 0; i < 4; ++i) rb[i] = bl(lrow + 64 * i, (kt_) * 64 + lck * 8); }
; #define G_STOREA(buf_) { bf16_t* nA = sA + (buf_) * 256 * GLD; _Pragma("unroll") for (int i = 0; i < 4; ++i) *(u32x4*)(nA + (lrow + 64 * i) * GLD + lck * 8) = ra[i]; }
; #define G_STOREB(buf_) { bf16_t* nB = sB + (buf_) * 256 * GLD; _Pragma("unroll") for (int i = 0; i < 4; ++i) *(u32x4*)(nB + (lrow + 64 * i) * GLD + lck * 8) = rb[i]; }
; template <class AL, class BL, class EP>
; DI void gemm_tile256(AL al, BL bl, EP ep, int K, char* smem) {
;   bf16_t* sA = (bf16_t*)smem;
;   bf16_t* sB = sA + 2 * 256 * GLD;
;   const int tid = tid512(), lane = tid & 63, w = tid >> 6, wm = w >> 2, wn = w & 3, r = lane & 31, h = lane >> 5;
;   const int lrow = tid >> 3, lck = tid & 7;
;   f32x16 acc[4][2];
; #pragma unroll
;   for (int i = 0; i < 4; ++i)
; #pragma unroll
;     for (int j = 0; j < 2; ++j)
; #pragma unroll
;       for (int q = 0; q < 16; ++q) acc[i][j][q] = 0.f;
;   u32x4 ra[4], rb[4];
;   const int KT = K >> 6;
;     ...
;   G_LOADA(0); G_LOADB(0);
;   __syncthreads();
;   G_STOREA(0); G_STOREB(0);
;   if (KT > 1) G_LOADB(1);
;   __syncthreads();
;   DI u32x4 operator()(int r, int k) const {
;     int row = row0 + r;
;     row = row < nrows ? row : nrows - 1;
;     return ldg16(base + (size_t)row * ld + k);
;   }
.LBB0_653:
	s_cmp_lg_u32 s14, 1
	s_mov_b64 s[0:1], -1
	s_cbranch_scc0 .LBB0_672
	v_mov_b32_e32 v42, v196
	v_readlane_b32 s40, v246, 17
	v_ashrrev_i32_e32 v43, 3, v42
	v_add_u32_e32 v12, s27, v43
	v_lshlrev_b32_e32 v0, 4, v42
	v_add_u32_e32 v26, s26, v43
	v_and_b32_e32 v160, 0x70, v0
	v_min_i32_e32 v44, 0x7fff, v12
	v_add_u32_e32 v2, 64, v12
	v_add_u32_e32 v10, 0x80, v12
	v_add_u32_e32 v12, 0xc0, v12
	v_add_u32_e32 v27, 0x80, v26
	v_lshl_add_u64 v[8:9], s[72:73], 0, v[160:161]
	v_min_i32_e32 v45, 0x7fff, v2
	v_min_i32_e32 v46, 0x7fff, v10
	v_min_i32_e32 v47, 0x7fff, v12
	v_lshl_add_u64 v[24:25], s[2:3], 0, v[160:161]
	v_min_i32_e32 v48, 0x3ff, v26
	v_add_u32_e32 v16, 64, v26
	v_min_i32_e32 v50, 0x3ff, v27
	v_add_u32_e32 v26, 0xc0, v26
	v_mad_i64_i32 v[0:1], s[0:1], v44, s17, v[8:9]
	v_mad_i64_i32 v[4:5], s[0:1], v45, s17, v[8:9]
	v_mad_i64_i32 v[10:11], s[0:1], v46, s17, v[8:9]
	v_mad_i64_i32 v[12:13], s[0:1], v47, s17, v[8:9]
	v_mad_i64_i32 v[32:33], s[0:1], v48, s17, v[24:25]
	v_min_i32_e32 v49, 0x3ff, v16
	v_mad_i64_i32 v[36:37], s[0:1], v50, s17, v[24:25]
	v_min_i32_e32 v51, 0x3ff, v26
	v_mov_b32_e32 v254, v0
	v_mov_b32_e32 v255, v1
	s_nop 0
	s_nop 0
	s_nop 0
	v_mad_i64_i32 v[34:35], s[0:1], v49, s17, v[24:25]
	v_mov_b32_e32 v252, v32
	v_mov_b32_e32 v253, v33
	v_mad_i64_i32 v[38:39], s[0:1], v51, s17, v[24:25]
	v_bfe_u32 v198, v42, 6, 2
	v_and_b32_e32 v52, 31, v42
	v_ashrrev_i32_e32 v53, 1, v42
	v_lshrrev_b32_e32 v42, 2, v42
	v_mul_lo_u32 v43, v43, s18
	v_and_or_b32 v199, v53, s19, v52
	v_and_b32_e32 v200, 8, v42
	v_lshl_or_b32 v52, v198, 6, v52
	v_readlane_b32 s54, v246, 31
	v_readlane_b32 s55, v246, 32
	v_add_u32_e32 v201, v160, v43
	v_or_b32_e32 v53, 0x12000, v160
	v_lshlrev_b32_e32 v42, 1, v200
	v_mul_u32_u24_e32 v52, 0x48, v52
	v_mov_b64_e32 v[40:41], s[54:55]
	v_or_b32_e32 v54, 0x1b000, v160
	v_add_u32_e32 v202, v53, v43
	v_mad_u64_u32 v[162:163], s[0:1], v199, s18, v[42:43]
	v_lshl_add_u32 v42, v52, 1, v42
	v_mad_i64_i32 v[164:165], s[0:1], v48, s17, v[40:41]
	v_add_u32_e32 v163, 0x12000, v42
	v_add_u32_e32 v203, 0x1b000, v42
	v_mad_i64_i32 v[166:167], s[0:1], v49, s17, v[40:41]
	v_mad_i64_i32 v[168:169], s[0:1], v50, s17, v[40:41]
	v_mad_i64_i32 v[170:171], s[0:1], v51, s17, v[40:41]
	v_mad_i64_i32 v[172:173], s[0:1], v44, s17, v[40:41]
	v_mad_i64_i32 v[174:175], s[0:1], v45, s17, v[40:41]
	v_mad_i64_i32 v[176:177], s[0:1], v46, s17, v[40:41]
	v_mad_i64_i32 v[178:179], s[0:1], v47, s17, v[40:41]
	s_mov_b32 s28, 0
	v_add_u32_e32 v204, v54, v43
	v_readlane_b32 s41, v246, 18
	v_readlane_b32 s42, v246, 19
	v_readlane_b32 s43, v246, 20
	v_readlane_b32 s44, v246, 21
	v_readlane_b32 s45, v246, 22
	v_readlane_b32 s46, v246, 23
	v_readlane_b32 s47, v246, 24
	v_readlane_b32 s48, v246, 25
	v_readlane_b32 s49, v246, 26
	v_readlane_b32 s50, v246, 27
	v_readlane_b32 s51, v246, 28
	v_readlane_b32 s52, v246, 29
	v_readlane_b32 s53, v246, 30
	v_lshrrev_b32_e32 v228, 6, v196
	s_mov_b32 s6, 64
	v_readfirstlane_b32 s29, v228
	s_mov_b32 s7, 0
	s_mov_b32 s10, 0xb0000
	s_mov_b32 s11, 0
	v_bfe_u32 v226, v196, 2, 4
	s_lshl_b32 s30, s29, 3
	v_add_u32_e32 v226, s30, v226
	s_mov_b32 s30, 0x1600
	v_mul_lo_u32 v226, v226, s30
	v_bfe_u32 v228, v196, 4, 2
	v_and_b32_e32 v227, 3, v196
	v_xor_b32_e32 v228, v227, v228
	v_lshl_add_u32 v226, v228, 4, v226
	v_mov_b32_e32 v227, 0
	v_readlane_b32 s14, v254, 0
	v_readlane_b32 s15, v255, 0
	s_nop 1
	v_lshl_add_u64 v[218:219], s[14:15], 0, v[226:227]
	v_lshl_add_u64 v[220:221], v[218:219], 0, s[10:11]
	v_readlane_b32 s14, v252, 0
	v_readlane_b32 s15, v253, 0
	s_nop 1
	v_lshl_add_u64 v[222:223], s[14:15], 0, v[226:227]
	v_lshl_add_u64 v[224:225], v[222:223], 0, s[10:11]
	v_and_b32_e32 v226, 31, v196
	v_bfe_u32 v228, v196, 2, 2
	v_bfe_u32 v227, v196, 5, 1
	v_xor_b32_e32 v228, v227, v228
	v_lshlrev_b32_e32 v228, 4, v228
	v_lshl_or_b32 v226, v226, 6, v228
	s_lshr_b32 s30, s29, 2
	s_lshl_b32 s30, s30, 13
	v_add_u32_e32 v128, s30, v226
	s_and_b32 s30, s29, 3
	s_lshl_b32 s30, s30, 12
	s_add_u32 s30, s30, 0x4000
	v_add_u32_e32 v131, s30, v226
	v_xor_b32_e32 v130, 0x20, v128
	v_xor_b32_e32 v205, 0x20, v131
	v_add_u32_e32 v206, 0x10000, v128
	v_add_u32_e32 v212, 0x10000, v131
	v_add_u32_e32 v214, 0x20000, v128
	v_add_u32_e32 v216, 0x20000, v131
	v_add_u32_e32 v207, 0x10000, v130
	v_add_u32_e32 v213, 0x10000, v205
	v_add_u32_e32 v215, 0x20000, v130
	v_add_u32_e32 v217, 0x20000, v205
	s_lshl_b32 s29, s29, 10
	s_waitcnt lgkmcnt(0)
	s_barrier
; #define G_LOADA(kt_) { _Pragma("unroll") for (int i = 0; i < 4; ++i) ra[i] = al(lrow + 64 * i, (kt_) * 64 + lck * 8); }
; #define G_LOADB(kt_) { _Pragma("unroll") for (int i = 0; i < 4; ++i) rb[i] = bl(lrow + 64 * i, (kt_) * 64 + lck * 8); }
; #define G_STOREA(buf_) { bf16_t* nA = sA + (buf_) * 256 * GLD; _Pragma("unroll") for (int i = 0; i < 4; ++i) *(u32x4*)(nA + (lrow + 64 * i) * GLD + lck * 8) = ra[i]; }
; #define G_STOREB(buf_) { bf16_t* nB = sB + (buf_) * 256 * GLD; _Pragma("unroll") for (int i = 0; i < 4; ++i) *(u32x4*)(nB + (lrow + 64 * i) * GLD + lck * 8) = rb[i]; }
; template <class AL, class BL, class EP>
; DI void gemm_tile256(AL al, BL bl, EP ep, int K, char* smem) {
;     ...
;   f32x16 acc[4][2];
; #pragma unroll
;   for (int i = 0; i < 4; ++i)
; #pragma unroll
;     for (int j = 0; j < 2; ++j)
; #pragma unroll
;       for (int q = 0; q < 16; ++q) acc[i][j][q] = 0.f;
;     ...
;   G_LOADA(0); G_LOADB(0);
;   __syncthreads();
;   G_STOREA(0); G_STOREB(0);
;   if (KT > 1) G_LOADB(1);
;   __syncthreads();
	s_add_u32 m0, s29, 0x0
	s_nop 0
	global_load_lds_dwordx4 v[218:219], off
	v_lshl_add_u64 v[218:219], v[218:219], 0, s[6:7]
	s_add_u32 m0, s29, 0x4000
	s_nop 0
	global_load_lds_dwordx4 v[222:223], off
	v_lshl_add_u64 v[222:223], v[222:223], 0, s[6:7]
	s_add_u32 m0, s29, 0x2000
	s_nop 0
	global_load_lds_dwordx4 v[220:221], off
	v_lshl_add_u64 v[220:221], v[220:221], 0, s[6:7]
	s_add_u32 m0, s29, 0x6000
	s_nop 0
	global_load_lds_dwordx4 v[224:225], off
	v_lshl_add_u64 v[224:225], v[224:225], 0, s[6:7]
	s_add_u32 m0, s29, 0x8000
	s_nop 0
	global_load_lds_dwordx4 v[218:219], off
	v_lshl_add_u64 v[218:219], v[218:219], 0, s[6:7]
	s_add_u32 m0, s29, 0xc000
	s_nop 0
	global_load_lds_dwordx4 v[222:223], off
	v_lshl_add_u64 v[222:223], v[222:223], 0, s[6:7]
	s_add_u32 m0, s29, 0xa000
	s_nop 0
	global_load_lds_dwordx4 v[220:221], off
	v_lshl_add_u64 v[220:221], v[220:221], 0, s[6:7]
	s_add_u32 m0, s29, 0xe000
	s_nop 0
	global_load_lds_dwordx4 v[224:225], off
	v_lshl_add_u64 v[224:225], v[224:225], 0, s[6:7]
	s_add_u32 m0, s29, 0x10000
	s_nop 0
	global_load_lds_dwordx4 v[218:219], off
	v_lshl_add_u64 v[218:219], v[218:219], 0, s[6:7]
	s_add_u32 m0, s29, 0x14000
	s_nop 0
	global_load_lds_dwordx4 v[222:223], off
	v_lshl_add_u64 v[222:223], v[222:223], 0, s[6:7]
	s_add_u32 m0, s29, 0x12000
	s_nop 0
	global_load_lds_dwordx4 v[220:221], off
	v_lshl_add_u64 v[220:221], v[220:221], 0, s[6:7]
	s_add_u32 m0, s29, 0x16000
	s_nop 0
	global_load_lds_dwordx4 v[224:225], off
	v_lshl_add_u64 v[224:225], v[224:225], 0, s[6:7]
	s_add_u32 m0, s29, 0x18000
	s_nop 0
	global_load_lds_dwordx4 v[218:219], off
	v_lshl_add_u64 v[218:219], v[218:219], 0, s[6:7]
	s_add_u32 m0, s29, 0x1c000
	s_nop 0
	global_load_lds_dwordx4 v[222:223], off
	v_lshl_add_u64 v[222:223], v[222:223], 0, s[6:7]
	s_add_u32 m0, s29, 0x1a000
	s_nop 0
	global_load_lds_dwordx4 v[220:221], off
	v_lshl_add_u64 v[220:221], v[220:221], 0, s[6:7]
	s_add_u32 m0, s29, 0x1e000
	s_nop 0
	global_load_lds_dwordx4 v[224:225], off
	v_lshl_add_u64 v[224:225], v[224:225], 0, s[6:7]
	s_add_u32 m0, s29, 0x20000
	s_nop 0
	global_load_lds_dwordx4 v[218:219], off
	v_lshl_add_u64 v[218:219], v[218:219], 0, s[6:7]
	s_add_u32 m0, s29, 0x24000
	s_nop 0
	global_load_lds_dwordx4 v[222:223], off
	v_lshl_add_u64 v[222:223], v[222:223], 0, s[6:7]
	v_mov_b64_e32 v[112:113], 0
	v_mov_b64_e32 v[114:115], 0
	v_mov_b64_e32 v[116:117], 0
	v_mov_b64_e32 v[118:119], 0
	v_mov_b64_e32 v[120:121], 0
	v_mov_b64_e32 v[122:123], 0
	v_mov_b64_e32 v[124:125], 0
	v_mov_b64_e32 v[126:127], 0
	v_mov_b64_e32 v[96:97], 0
	v_mov_b64_e32 v[98:99], 0
	v_mov_b64_e32 v[100:101], 0
	v_mov_b64_e32 v[102:103], 0
	v_mov_b64_e32 v[104:105], 0
	v_mov_b64_e32 v[106:107], 0
	v_mov_b64_e32 v[108:109], 0
	v_mov_b64_e32 v[110:111], 0
	v_mov_b64_e32 v[80:81], 0
	v_mov_b64_e32 v[82:83], 0
	v_mov_b64_e32 v[84:85], 0
	v_mov_b64_e32 v[86:87], 0
	v_mov_b64_e32 v[88:89], 0
	v_mov_b64_e32 v[90:91], 0
	v_mov_b64_e32 v[92:93], 0
	v_mov_b64_e32 v[94:95], 0
	v_mov_b64_e32 v[64:65], 0
	v_mov_b64_e32 v[66:67], 0
	v_mov_b64_e32 v[68:69], 0
	v_mov_b64_e32 v[70:71], 0
	v_mov_b64_e32 v[72:73], 0
	v_mov_b64_e32 v[74:75], 0
	v_mov_b64_e32 v[76:77], 0
	v_mov_b64_e32 v[78:79], 0
	v_mov_b64_e32 v[48:49], 0
	v_mov_b64_e32 v[50:51], 0
	v_mov_b64_e32 v[52:53], 0
	v_mov_b64_e32 v[54:55], 0
	v_mov_b64_e32 v[56:57], 0
	v_mov_b64_e32 v[58:59], 0
	v_mov_b64_e32 v[60:61], 0
	v_mov_b64_e32 v[62:63], 0
	v_mov_b64_e32 v[32:33], 0
	v_mov_b64_e32 v[34:35], 0
	v_mov_b64_e32 v[36:37], 0
	v_mov_b64_e32 v[38:39], 0
	v_mov_b64_e32 v[40:41], 0
	v_mov_b64_e32 v[42:43], 0
	v_mov_b64_e32 v[44:45], 0
	v_mov_b64_e32 v[46:47], 0
	v_mov_b64_e32 v[16:17], 0
	v_mov_b64_e32 v[18:19], 0
	v_mov_b64_e32 v[20:21], 0
	v_mov_b64_e32 v[22:23], 0
	v_mov_b64_e32 v[24:25], 0
	v_mov_b64_e32 v[26:27], 0
	v_mov_b64_e32 v[28:29], 0
	v_mov_b64_e32 v[30:31], 0
	v_mov_b64_e32 v[0:1], 0
	v_mov_b64_e32 v[2:3], 0
	v_mov_b64_e32 v[4:5], 0
	v_mov_b64_e32 v[6:7], 0
	v_mov_b64_e32 v[8:9], 0
	v_mov_b64_e32 v[10:11], 0
	v_mov_b64_e32 v[12:13], 0
	v_mov_b64_e32 v[14:15], 0
	s_mov_b32 s30, 16
	s_waitcnt vmcnt(14)
	s_barrier
	ds_read_b128 v[184:187], v131
	ds_read_b128 v[132:135], v128
	ds_read_b128 v[188:191], v131 offset:2048
	ds_read_b128 v[136:139], v128 offset:2048
	ds_read_b128 v[140:143], v128 offset:4096
	ds_read_b128 v[144:147], v128 offset:6144
; template <class AL, class BL, class EP>
; DI void gemm_tile256(AL al, BL bl, EP ep, int K, char* smem) {
;     ...
;   for (int kt = 0; kt < KT; kt += 2) {
;     G_STEP(0, kt);
;     if (kt + 1 >= KT) break;
;     G_STEP(1, kt + 1);
;   }
.Lgk_ph7_loop:
	s_waitcnt lgkmcnt(0)
	v_mfma_f32_32x32x16_bf16 v[112:127], v[184:187], v[132:135], v[112:127]
	ds_read_b128 v[192:195], v205
	ds_read_b128 v[148:151], v130
	v_mfma_f32_32x32x16_bf16 v[96:111], v[188:191], v[132:135], v[96:111]
	ds_read_b128 v[208:211], v205 offset:2048
	ds_read_b128 v[152:155], v130 offset:2048
	v_mfma_f32_32x32x16_bf16 v[80:95], v[184:187], v[136:139], v[80:95]
	ds_read_b128 v[156:159], v130 offset:4096
	ds_read_b128 v[180:183], v130 offset:6144
	v_mfma_f32_32x32x16_bf16 v[64:79], v[188:191], v[136:139], v[64:79]
	s_add_u32 m0, s29, 0x22000
	s_nop 0
	global_load_lds_dwordx4 v[220:221], off
	v_lshl_add_u64 v[220:221], v[220:221], 0, s[6:7]
	v_mfma_f32_32x32x16_bf16 v[48:63], v[184:187], v[140:143], v[48:63]
	v_mfma_f32_32x32x16_bf16 v[32:47], v[188:191], v[140:143], v[32:47]
	v_mfma_f32_32x32x16_bf16 v[16:31], v[184:187], v[144:147], v[16:31]
	v_mfma_f32_32x32x16_bf16 v[0:15], v[188:191], v[144:147], v[0:15]
	s_add_u32 m0, s29, 0x26000
	s_nop 0
	global_load_lds_dwordx4 v[224:225], off
	v_lshl_add_u64 v[224:225], v[224:225], 0, s[6:7]
	s_waitcnt lgkmcnt(0)
	s_waitcnt vmcnt(12)
	s_barrier
	s_waitcnt lgkmcnt(0)
	v_mfma_f32_32x32x16_bf16 v[112:127], v[192:195], v[148:151], v[112:127]
	ds_read_b128 v[184:187], v131 offset:32768
	ds_read_b128 v[132:135], v128 offset:32768
	v_mfma_f32_32x32x16_bf16 v[96:111], v[208:211], v[148:151], v[96:111]
	ds_read_b128 v[188:191], v131 offset:34816
	ds_read_b128 v[136:139], v128 offset:34816
	v_mfma_f32_32x32x16_bf16 v[80:95], v[192:195], v[152:155], v[80:95]
	ds_read_b128 v[140:143], v128 offset:36864
	ds_read_b128 v[144:147], v128 offset:38912
	v_mfma_f32_32x32x16_bf16 v[64:79], v[208:211], v[152:155], v[64:79]
	s_add_u32 m0, s29, 0x0
	s_nop 0
	global_load_lds_dwordx4 v[218:219], off
	v_lshl_add_u64 v[218:219], v[218:219], 0, s[6:7]
	v_mfma_f32_32x32x16_bf16 v[48:63], v[192:195], v[156:159], v[48:63]
	v_mfma_f32_32x32x16_bf16 v[32:47], v[208:211], v[156:159], v[32:47]
	v_mfma_f32_32x32x16_bf16 v[16:31], v[192:195], v[180:183], v[16:31]
	v_mfma_f32_32x32x16_bf16 v[0:15], v[208:211], v[180:183], v[0:15]
	s_add_u32 m0, s29, 0x4000
	s_nop 0
	global_load_lds_dwordx4 v[222:223], off
	v_lshl_add_u64 v[222:223], v[222:223], 0, s[6:7]
	s_waitcnt lgkmcnt(0)
	v_mfma_f32_32x32x16_bf16 v[112:127], v[184:187], v[132:135], v[112:127]
	ds_read_b128 v[192:195], v205 offset:32768
	ds_read_b128 v[148:151], v130 offset:32768
	v_mfma_f32_32x32x16_bf16 v[96:111], v[188:191], v[132:135], v[96:111]
	ds_read_b128 v[208:211], v205 offset:34816
	ds_read_b128 v[152:155], v130 offset:34816
	v_mfma_f32_32x32x16_bf16 v[80:95], v[184:187], v[136:139], v[80:95]
	ds_read_b128 v[156:159], v130 offset:36864
	ds_read_b128 v[180:183], v130 offset:38912
	v_mfma_f32_32x32x16_bf16 v[64:79], v[188:191], v[136:139], v[64:79]
	s_add_u32 m0, s29, 0x2000
	s_nop 0
	global_load_lds_dwordx4 v[220:221], off
	v_lshl_add_u64 v[220:221], v[220:221], 0, s[6:7]
	v_mfma_f32_32x32x16_bf16 v[48:63], v[184:187], v[140:143], v[48:63]
	v_mfma_f32_32x32x16_bf16 v[32:47], v[188:191], v[140:143], v[32:47]
	v_mfma_f32_32x32x16_bf16 v[16:31], v[184:187], v[144:147], v[16:31]
	v_mfma_f32_32x32x16_bf16 v[0:15], v[188:191], v[144:147], v[0:15]
	s_add_u32 m0, s29, 0x6000
	s_nop 0
	global_load_lds_dwordx4 v[224:225], off
	v_lshl_add_u64 v[224:225], v[224:225], 0, s[6:7]
	s_waitcnt lgkmcnt(0)
	s_waitcnt vmcnt(12)
	s_barrier
	s_waitcnt lgkmcnt(0)
	v_mfma_f32_32x32x16_bf16 v[112:127], v[192:195], v[148:151], v[112:127]
	ds_read_b128 v[184:187], v212
	ds_read_b128 v[132:135], v206
	v_mfma_f32_32x32x16_bf16 v[96:111], v[208:211], v[148:151], v[96:111]
	ds_read_b128 v[188:191], v212 offset:2048
	ds_read_b128 v[136:139], v206 offset:2048
	v_mfma_f32_32x32x16_bf16 v[80:95], v[192:195], v[152:155], v[80:95]
	ds_read_b128 v[140:143], v206 offset:4096
	ds_read_b128 v[144:147], v206 offset:6144
	v_mfma_f32_32x32x16_bf16 v[64:79], v[208:211], v[152:155], v[64:79]
	s_add_u32 m0, s29, 0x8000
	s_nop 0
	global_load_lds_dwordx4 v[218:219], off
	v_lshl_add_u64 v[218:219], v[218:219], 0, s[6:7]
	v_mfma_f32_32x32x16_bf16 v[48:63], v[192:195], v[156:159], v[48:63]
	v_mfma_f32_32x32x16_bf16 v[32:47], v[208:211], v[156:159], v[32:47]
	v_mfma_f32_32x32x16_bf16 v[16:31], v[192:195], v[180:183], v[16:31]
	v_mfma_f32_32x32x16_bf16 v[0:15], v[208:211], v[180:183], v[0:15]
	s_add_u32 m0, s29, 0xc000
	s_nop 0
	global_load_lds_dwordx4 v[222:223], off
	v_lshl_add_u64 v[222:223], v[222:223], 0, s[6:7]
	s_waitcnt lgkmcnt(0)
	v_mfma_f32_32x32x16_bf16 v[112:127], v[184:187], v[132:135], v[112:127]
	ds_read_b128 v[192:195], v213
	ds_read_b128 v[148:151], v207
	v_mfma_f32_32x32x16_bf16 v[96:111], v[188:191], v[132:135], v[96:111]
	ds_read_b128 v[208:211], v213 offset:2048
	ds_read_b128 v[152:155], v207 offset:2048
	v_mfma_f32_32x32x16_bf16 v[80:95], v[184:187], v[136:139], v[80:95]
	ds_read_b128 v[156:159], v207 offset:4096
	ds_read_b128 v[180:183], v207 offset:6144
	v_mfma_f32_32x32x16_bf16 v[64:79], v[188:191], v[136:139], v[64:79]
	s_add_u32 m0, s29, 0xa000
	s_nop 0
	global_load_lds_dwordx4 v[220:221], off
	v_lshl_add_u64 v[220:221], v[220:221], 0, s[6:7]
	v_mfma_f32_32x32x16_bf16 v[48:63], v[184:187], v[140:143], v[48:63]
	v_mfma_f32_32x32x16_bf16 v[32:47], v[188:191], v[140:143], v[32:47]
	v_mfma_f32_32x32x16_bf16 v[16:31], v[184:187], v[144:147], v[16:31]
	v_mfma_f32_32x32x16_bf16 v[0:15], v[188:191], v[144:147], v[0:15]
	s_add_u32 m0, s29, 0xe000
	s_nop 0
	global_load_lds_dwordx4 v[224:225], off
	v_lshl_add_u64 v[224:225], v[224:225], 0, s[6:7]
	s_waitcnt lgkmcnt(0)
	s_waitcnt vmcnt(12)
	s_barrier
; template <class AL, class BL, class EP>
; DI void gemm_tile256(AL al, BL bl, EP ep, int K, char* smem) {
;     ...
;   for (int kt = 0; kt < KT; kt += 2) {
;     G_STEP(0, kt);
;     if (kt + 1 >= KT) break;
;     G_STEP(1, kt + 1);
;   }
	s_waitcnt lgkmcnt(0)
	v_mfma_f32_32x32x16_bf16 v[112:127], v[192:195], v[148:151], v[112:127]
	ds_read_b128 v[184:187], v212 offset:32768
	ds_read_b128 v[132:135], v206 offset:32768
	v_mfma_f32_32x32x16_bf16 v[96:111], v[208:211], v[148:151], v[96:111]
	ds_read_b128 v[188:191], v212 offset:34816
	ds_read_b128 v[136:139], v206 offset:34816
	v_mfma_f32_32x32x16_bf16 v[80:95], v[192:195], v[152:155], v[80:95]
	ds_read_b128 v[140:143], v206 offset:36864
	ds_read_b128 v[144:147], v206 offset:38912
	v_mfma_f32_32x32x16_bf16 v[64:79], v[208:211], v[152:155], v[64:79]
	s_add_u32 m0, s29, 0x10000
	s_nop 0
	global_load_lds_dwordx4 v[218:219], off
	v_lshl_add_u64 v[218:219], v[218:219], 0, s[6:7]
	v_mfma_f32_32x32x16_bf16 v[48:63], v[192:195], v[156:159], v[48:63]
	v_mfma_f32_32x32x16_bf16 v[32:47], v[208:211], v[156:159], v[32:47]
	v_mfma_f32_32x32x16_bf16 v[16:31], v[192:195], v[180:183], v[16:31]
	v_mfma_f32_32x32x16_bf16 v[0:15], v[208:211], v[180:183], v[0:15]
	s_add_u32 m0, s29, 0x14000
	s_nop 0
	global_load_lds_dwordx4 v[222:223], off
	v_lshl_add_u64 v[222:223], v[222:223], 0, s[6:7]
	s_waitcnt lgkmcnt(0)
	v_mfma_f32_32x32x16_bf16 v[112:127], v[184:187], v[132:135], v[112:127]
	ds_read_b128 v[192:195], v213 offset:32768
	ds_read_b128 v[148:151], v207 offset:32768
	v_mfma_f32_32x32x16_bf16 v[96:111], v[188:191], v[132:135], v[96:111]
	ds_read_b128 v[208:211], v213 offset:34816
	ds_read_b128 v[152:155], v207 offset:34816
	v_mfma_f32_32x32x16_bf16 v[80:95], v[184:187], v[136:139], v[80:95]
	ds_read_b128 v[156:159], v207 offset:36864
	ds_read_b128 v[180:183], v207 offset:38912
	v_mfma_f32_32x32x16_bf16 v[64:79], v[188:191], v[136:139], v[64:79]
	s_add_u32 m0, s29, 0x12000
	s_nop 0
	global_load_lds_dwordx4 v[220:221], off
	v_lshl_add_u64 v[220:221], v[220:221], 0, s[6:7]
	v_mfma_f32_32x32x16_bf16 v[48:63], v[184:187], v[140:143], v[48:63]
	v_mfma_f32_32x32x16_bf16 v[32:47], v[188:191], v[140:143], v[32:47]
	v_mfma_f32_32x32x16_bf16 v[16:31], v[184:187], v[144:147], v[16:31]
	v_mfma_f32_32x32x16_bf16 v[0:15], v[188:191], v[144:147], v[0:15]
	s_add_u32 m0, s29, 0x16000
	s_nop 0
	global_load_lds_dwordx4 v[224:225], off
	v_lshl_add_u64 v[224:225], v[224:225], 0, s[6:7]
	s_waitcnt lgkmcnt(0)
	s_waitcnt vmcnt(12)
	s_barrier
	s_waitcnt lgkmcnt(0)
	v_mfma_f32_32x32x16_bf16 v[112:127], v[192:195], v[148:151], v[112:127]
	ds_read_b128 v[184:187], v216
	ds_read_b128 v[132:135], v214
	v_mfma_f32_32x32x16_bf16 v[96:111], v[208:211], v[148:151], v[96:111]
	ds_read_b128 v[188:191], v216 offset:2048
	ds_read_b128 v[136:139], v214 offset:2048
	v_mfma_f32_32x32x16_bf16 v[80:95], v[192:195], v[152:155], v[80:95]
	ds_read_b128 v[140:143], v214 offset:4096
	ds_read_b128 v[144:147], v214 offset:6144
	v_mfma_f32_32x32x16_bf16 v[64:79], v[208:211], v[152:155], v[64:79]
	s_add_u32 m0, s29, 0x18000
	s_nop 0
	global_load_lds_dwordx4 v[218:219], off
	v_lshl_add_u64 v[218:219], v[218:219], 0, s[6:7]
	v_mfma_f32_32x32x16_bf16 v[48:63], v[192:195], v[156:159], v[48:63]
	v_mfma_f32_32x32x16_bf16 v[32:47], v[208:211], v[156:159], v[32:47]
	v_mfma_f32_32x32x16_bf16 v[16:31], v[192:195], v[180:183], v[16:31]
	v_mfma_f32_32x32x16_bf16 v[0:15], v[208:211], v[180:183], v[0:15]
	s_add_u32 m0, s29, 0x1c000
	s_nop 0
	global_load_lds_dwordx4 v[222:223], off
	v_lshl_add_u64 v[222:223], v[222:223], 0, s[6:7]
	s_waitcnt lgkmcnt(0)
	v_mfma_f32_32x32x16_bf16 v[112:127], v[184:187], v[132:135], v[112:127]
	ds_read_b128 v[192:195], v217
	ds_read_b128 v[148:151], v215
	v_mfma_f32_32x32x16_bf16 v[96:111], v[188:191], v[132:135], v[96:111]
	ds_read_b128 v[208:211], v217 offset:2048
	ds_read_b128 v[152:155], v215 offset:2048
	v_mfma_f32_32x32x16_bf16 v[80:95], v[184:187], v[136:139], v[80:95]
	ds_read_b128 v[156:159], v215 offset:4096
	ds_read_b128 v[180:183], v215 offset:6144
	v_mfma_f32_32x32x16_bf16 v[64:79], v[188:191], v[136:139], v[64:79]
	s_add_u32 m0, s29, 0x1a000
	s_nop 0
	global_load_lds_dwordx4 v[220:221], off
	v_lshl_add_u64 v[220:221], v[220:221], 0, s[6:7]
	v_mfma_f32_32x32x16_bf16 v[48:63], v[184:187], v[140:143], v[48:63]
	v_mfma_f32_32x32x16_bf16 v[32:47], v[188:191], v[140:143], v[32:47]
	v_mfma_f32_32x32x16_bf16 v[16:31], v[184:187], v[144:147], v[16:31]
	v_mfma_f32_32x32x16_bf16 v[0:15], v[188:191], v[144:147], v[0:15]
	s_add_u32 m0, s29, 0x1e000
	s_nop 0
	global_load_lds_dwordx4 v[224:225], off
	v_lshl_add_u64 v[224:225], v[224:225], 0, s[6:7]
	s_waitcnt lgkmcnt(0)
	s_waitcnt vmcnt(12)
	s_barrier
	s_waitcnt lgkmcnt(0)
	v_mfma_f32_32x32x16_bf16 v[112:127], v[192:195], v[148:151], v[112:127]
	ds_read_b128 v[184:187], v131
	ds_read_b128 v[132:135], v128
	v_mfma_f32_32x32x16_bf16 v[96:111], v[208:211], v[148:151], v[96:111]
	ds_read_b128 v[188:191], v131 offset:2048
	ds_read_b128 v[136:139], v128 offset:2048
	v_mfma_f32_32x32x16_bf16 v[80:95], v[192:195], v[152:155], v[80:95]
	ds_read_b128 v[140:143], v128 offset:4096
	ds_read_b128 v[144:147], v128 offset:6144
	v_mfma_f32_32x32x16_bf16 v[64:79], v[208:211], v[152:155], v[64:79]
	s_add_u32 m0, s29, 0x20000
	s_nop 0
	global_load_lds_dwordx4 v[218:219], off
	v_lshl_add_u64 v[218:219], v[218:219], 0, s[6:7]
	v_mfma_f32_32x32x16_bf16 v[48:63], v[192:195], v[156:159], v[48:63]
	v_mfma_f32_32x32x16_bf16 v[32:47], v[208:211], v[156:159], v[32:47]
	v_mfma_f32_32x32x16_bf16 v[16:31], v[192:195], v[180:183], v[16:31]
	v_mfma_f32_32x32x16_bf16 v[0:15], v[208:211], v[180:183], v[0:15]
	s_add_u32 m0, s29, 0x24000
	s_nop 0
	global_load_lds_dwordx4 v[222:223], off
	v_lshl_add_u64 v[222:223], v[222:223], 0, s[6:7]
	s_sub_u32 s30, s30, 1
	s_cmp_lg_u32 s30, 0
	s_cbranch_scc1 .Lgk_ph7_loop
; template <class AL, class BL, class EP>
; DI void gemm_tile256(AL al, BL bl, EP ep, int K, char* smem) {
;     ...
;   for (int kt = 0; kt < KT; kt += 2) {
;     G_STEP(0, kt);
;     if (kt + 1 >= KT) break;
;     G_STEP(1, kt + 1);
;   }
	s_waitcnt lgkmcnt(0)
	v_mfma_f32_32x32x16_bf16 v[112:127], v[184:187], v[132:135], v[112:127]
	ds_read_b128 v[192:195], v205
	ds_read_b128 v[148:151], v130
	v_mfma_f32_32x32x16_bf16 v[96:111], v[188:191], v[132:135], v[96:111]
	ds_read_b128 v[208:211], v205 offset:2048
	ds_read_b128 v[152:155], v130 offset:2048
	v_mfma_f32_32x32x16_bf16 v[80:95], v[184:187], v[136:139], v[80:95]
	ds_read_b128 v[156:159], v130 offset:4096
	ds_read_b128 v[180:183], v130 offset:6144
	v_mfma_f32_32x32x16_bf16 v[64:79], v[188:191], v[136:139], v[64:79]
	s_add_u32 m0, s29, 0x22000
	s_nop 0
	global_load_lds_dwordx4 v[220:221], off
	v_lshl_add_u64 v[220:221], v[220:221], 0, s[6:7]
	v_mfma_f32_32x32x16_bf16 v[48:63], v[184:187], v[140:143], v[48:63]
	v_mfma_f32_32x32x16_bf16 v[32:47], v[188:191], v[140:143], v[32:47]
	v_mfma_f32_32x32x16_bf16 v[16:31], v[184:187], v[144:147], v[16:31]
	v_mfma_f32_32x32x16_bf16 v[0:15], v[188:191], v[144:147], v[0:15]
	s_add_u32 m0, s29, 0x26000
	s_nop 0
	global_load_lds_dwordx4 v[224:225], off
	v_lshl_add_u64 v[224:225], v[224:225], 0, s[6:7]
	s_waitcnt lgkmcnt(0)
	s_waitcnt vmcnt(12)
	s_barrier
	s_waitcnt lgkmcnt(0)
	v_mfma_f32_32x32x16_bf16 v[112:127], v[192:195], v[148:151], v[112:127]
	ds_read_b128 v[184:187], v131 offset:32768
	ds_read_b128 v[132:135], v128 offset:32768
	v_mfma_f32_32x32x16_bf16 v[96:111], v[208:211], v[148:151], v[96:111]
	ds_read_b128 v[188:191], v131 offset:34816
	ds_read_b128 v[136:139], v128 offset:34816
	v_mfma_f32_32x32x16_bf16 v[80:95], v[192:195], v[152:155], v[80:95]
	ds_read_b128 v[140:143], v128 offset:36864
	ds_read_b128 v[144:147], v128 offset:38912
	v_mfma_f32_32x32x16_bf16 v[64:79], v[208:211], v[152:155], v[64:79]
	s_add_u32 m0, s29, 0x0
	s_nop 0
	global_load_lds_dwordx4 v[218:219], off
	v_lshl_add_u64 v[218:219], v[218:219], 0, s[6:7]
	v_mfma_f32_32x32x16_bf16 v[48:63], v[192:195], v[156:159], v[48:63]
	v_mfma_f32_32x32x16_bf16 v[32:47], v[208:211], v[156:159], v[32:47]
	v_mfma_f32_32x32x16_bf16 v[16:31], v[192:195], v[180:183], v[16:31]
	v_mfma_f32_32x32x16_bf16 v[0:15], v[208:211], v[180:183], v[0:15]
	s_add_u32 m0, s29, 0x4000
	s_nop 0
	global_load_lds_dwordx4 v[222:223], off
	v_lshl_add_u64 v[222:223], v[222:223], 0, s[6:7]
	s_waitcnt lgkmcnt(0)
	v_mfma_f32_32x32x16_bf16 v[112:127], v[184:187], v[132:135], v[112:127]
	ds_read_b128 v[192:195], v205 offset:32768
	ds_read_b128 v[148:151], v130 offset:32768
	v_mfma_f32_32x32x16_bf16 v[96:111], v[188:191], v[132:135], v[96:111]
	ds_read_b128 v[208:211], v205 offset:34816
	ds_read_b128 v[152:155], v130 offset:34816
	v_mfma_f32_32x32x16_bf16 v[80:95], v[184:187], v[136:139], v[80:95]
	ds_read_b128 v[156:159], v130 offset:36864
	ds_read_b128 v[180:183], v130 offset:38912
	v_mfma_f32_32x32x16_bf16 v[64:79], v[188:191], v[136:139], v[64:79]
	s_add_u32 m0, s29, 0x2000
	s_nop 0
	global_load_lds_dwordx4 v[220:221], off
	v_lshl_add_u64 v[220:221], v[220:221], 0, s[6:7]
	v_mfma_f32_32x32x16_bf16 v[48:63], v[184:187], v[140:143], v[48:63]
	v_mfma_f32_32x32x16_bf16 v[32:47], v[188:191], v[140:143], v[32:47]
	v_mfma_f32_32x32x16_bf16 v[16:31], v[184:187], v[144:147], v[16:31]
	v_mfma_f32_32x32x16_bf16 v[0:15], v[188:191], v[144:147], v[0:15]
	s_add_u32 m0, s29, 0x6000
	s_nop 0
	global_load_lds_dwordx4 v[224:225], off
	v_lshl_add_u64 v[224:225], v[224:225], 0, s[6:7]
	s_waitcnt lgkmcnt(0)
	s_waitcnt vmcnt(12)
	s_barrier
	s_waitcnt lgkmcnt(0)
	v_mfma_f32_32x32x16_bf16 v[112:127], v[192:195], v[148:151], v[112:127]
	ds_read_b128 v[184:187], v212
	ds_read_b128 v[132:135], v206
	v_mfma_f32_32x32x16_bf16 v[96:111], v[208:211], v[148:151], v[96:111]
	ds_read_b128 v[188:191], v212 offset:2048
	ds_read_b128 v[136:139], v206 offset:2048
	v_mfma_f32_32x32x16_bf16 v[80:95], v[192:195], v[152:155], v[80:95]
	ds_read_b128 v[140:143], v206 offset:4096
	ds_read_b128 v[144:147], v206 offset:6144
	v_mfma_f32_32x32x16_bf16 v[64:79], v[208:211], v[152:155], v[64:79]
	s_add_u32 m0, s29, 0x8000
	s_nop 0
	global_load_lds_dwordx4 v[218:219], off
	v_lshl_add_u64 v[218:219], v[218:219], 0, s[6:7]
	v_mfma_f32_32x32x16_bf16 v[48:63], v[192:195], v[156:159], v[48:63]
	v_mfma_f32_32x32x16_bf16 v[32:47], v[208:211], v[156:159], v[32:47]
	v_mfma_f32_32x32x16_bf16 v[16:31], v[192:195], v[180:183], v[16:31]
	v_mfma_f32_32x32x16_bf16 v[0:15], v[208:211], v[180:183], v[0:15]
	s_add_u32 m0, s29, 0xc000
	s_nop 0
	global_load_lds_dwordx4 v[222:223], off
	v_lshl_add_u64 v[222:223], v[222:223], 0, s[6:7]
	s_waitcnt lgkmcnt(0)
	v_mfma_f32_32x32x16_bf16 v[112:127], v[184:187], v[132:135], v[112:127]
	ds_read_b128 v[192:195], v213
	ds_read_b128 v[148:151], v207
	v_mfma_f32_32x32x16_bf16 v[96:111], v[188:191], v[132:135], v[96:111]
	ds_read_b128 v[208:211], v213 offset:2048
	ds_read_b128 v[152:155], v207 offset:2048
	v_mfma_f32_32x32x16_bf16 v[80:95], v[184:187], v[136:139], v[80:95]
	ds_read_b128 v[156:159], v207 offset:4096
	ds_read_b128 v[180:183], v207 offset:6144
	v_mfma_f32_32x32x16_bf16 v[64:79], v[188:191], v[136:139], v[64:79]
	s_add_u32 m0, s29, 0xa000
	s_nop 0
	global_load_lds_dwordx4 v[220:221], off
	v_lshl_add_u64 v[220:221], v[220:221], 0, s[6:7]
	v_mfma_f32_32x32x16_bf16 v[48:63], v[184:187], v[140:143], v[48:63]
	v_mfma_f32_32x32x16_bf16 v[32:47], v[188:191], v[140:143], v[32:47]
	v_mfma_f32_32x32x16_bf16 v[16:31], v[184:187], v[144:147], v[16:31]
	v_mfma_f32_32x32x16_bf16 v[0:15], v[188:191], v[144:147], v[0:15]
	s_add_u32 m0, s29, 0xe000
	s_nop 0
	global_load_lds_dwordx4 v[224:225], off
	v_lshl_add_u64 v[224:225], v[224:225], 0, s[6:7]
	s_waitcnt lgkmcnt(0)
	s_waitcnt vmcnt(12)
	s_barrier
; template <class AL, class BL, class EP>
; DI void gemm_tile256(AL al, BL bl, EP ep, int K, char* smem) {
;     ...
;   for (int kt = 0; kt < KT; kt += 2) {
;     G_STEP(0, kt);
;     if (kt + 1 >= KT) break;
;     G_STEP(1, kt + 1);
;   }
	s_waitcnt lgkmcnt(0)
	v_mfma_f32_32x32x16_bf16 v[112:127], v[192:195], v[148:151], v[112:127]
	ds_read_b128 v[184:187], v212 offset:32768
	ds_read_b128 v[132:135], v206 offset:32768
	v_mfma_f32_32x32x16_bf16 v[96:111], v[208:211], v[148:151], v[96:111]
	ds_read_b128 v[188:191], v212 offset:34816
	ds_read_b128 v[136:139], v206 offset:34816
	v_mfma_f32_32x32x16_bf16 v[80:95], v[192:195], v[152:155], v[80:95]
	ds_read_b128 v[140:143], v206 offset:36864
	ds_read_b128 v[144:147], v206 offset:38912
	v_mfma_f32_32x32x16_bf16 v[64:79], v[208:211], v[152:155], v[64:79]
	s_add_u32 m0, s29, 0x10000
	s_nop 0
	global_load_lds_dwordx4 v[218:219], off
	v_lshl_add_u64 v[218:219], v[218:219], 0, s[6:7]
	v_mfma_f32_32x32x16_bf16 v[48:63], v[192:195], v[156:159], v[48:63]
	v_mfma_f32_32x32x16_bf16 v[32:47], v[208:211], v[156:159], v[32:47]
	v_mfma_f32_32x32x16_bf16 v[16:31], v[192:195], v[180:183], v[16:31]
	v_mfma_f32_32x32x16_bf16 v[0:15], v[208:211], v[180:183], v[0:15]
	s_add_u32 m0, s29, 0x14000
	s_nop 0
	global_load_lds_dwordx4 v[222:223], off
	v_lshl_add_u64 v[222:223], v[222:223], 0, s[6:7]
	s_waitcnt lgkmcnt(0)
	v_mfma_f32_32x32x16_bf16 v[112:127], v[184:187], v[132:135], v[112:127]
	ds_read_b128 v[192:195], v213 offset:32768
	ds_read_b128 v[148:151], v207 offset:32768
	v_mfma_f32_32x32x16_bf16 v[96:111], v[188:191], v[132:135], v[96:111]
	ds_read_b128 v[208:211], v213 offset:34816
	ds_read_b128 v[152:155], v207 offset:34816
	v_mfma_f32_32x32x16_bf16 v[80:95], v[184:187], v[136:139], v[80:95]
	ds_read_b128 v[156:159], v207 offset:36864
	ds_read_b128 v[180:183], v207 offset:38912
	v_mfma_f32_32x32x16_bf16 v[64:79], v[188:191], v[136:139], v[64:79]
	s_add_u32 m0, s29, 0x12000
	s_nop 0
	global_load_lds_dwordx4 v[220:221], off
	v_lshl_add_u64 v[220:221], v[220:221], 0, s[6:7]
	v_mfma_f32_32x32x16_bf16 v[48:63], v[184:187], v[140:143], v[48:63]
	v_mfma_f32_32x32x16_bf16 v[32:47], v[188:191], v[140:143], v[32:47]
	v_mfma_f32_32x32x16_bf16 v[16:31], v[184:187], v[144:147], v[16:31]
	v_mfma_f32_32x32x16_bf16 v[0:15], v[188:191], v[144:147], v[0:15]
	s_add_u32 m0, s29, 0x16000
	s_nop 0
	global_load_lds_dwordx4 v[224:225], off
	v_lshl_add_u64 v[224:225], v[224:225], 0, s[6:7]
	s_waitcnt lgkmcnt(0)
	s_waitcnt vmcnt(12)
	s_barrier
	s_waitcnt lgkmcnt(0)
	v_mfma_f32_32x32x16_bf16 v[112:127], v[192:195], v[148:151], v[112:127]
	ds_read_b128 v[184:187], v216
	ds_read_b128 v[132:135], v214
	v_mfma_f32_32x32x16_bf16 v[96:111], v[208:211], v[148:151], v[96:111]
	ds_read_b128 v[188:191], v216 offset:2048
	ds_read_b128 v[136:139], v214 offset:2048
	v_mfma_f32_32x32x16_bf16 v[80:95], v[192:195], v[152:155], v[80:95]
	ds_read_b128 v[140:143], v214 offset:4096
	ds_read_b128 v[144:147], v214 offset:6144
	v_mfma_f32_32x32x16_bf16 v[64:79], v[208:211], v[152:155], v[64:79]
	v_mfma_f32_32x32x16_bf16 v[48:63], v[192:195], v[156:159], v[48:63]
	v_mfma_f32_32x32x16_bf16 v[32:47], v[208:211], v[156:159], v[32:47]
	v_mfma_f32_32x32x16_bf16 v[16:31], v[192:195], v[180:183], v[16:31]
	v_mfma_f32_32x32x16_bf16 v[0:15], v[208:211], v[180:183], v[0:15]
	s_waitcnt lgkmcnt(0)
	v_mfma_f32_32x32x16_bf16 v[112:127], v[184:187], v[132:135], v[112:127]
	ds_read_b128 v[192:195], v217
	ds_read_b128 v[148:151], v215
	v_mfma_f32_32x32x16_bf16 v[96:111], v[188:191], v[132:135], v[96:111]
	ds_read_b128 v[208:211], v217 offset:2048
	ds_read_b128 v[152:155], v215 offset:2048
	v_mfma_f32_32x32x16_bf16 v[80:95], v[184:187], v[136:139], v[80:95]
	ds_read_b128 v[156:159], v215 offset:4096
	ds_read_b128 v[180:183], v215 offset:6144
	v_mfma_f32_32x32x16_bf16 v[64:79], v[188:191], v[136:139], v[64:79]
	v_mfma_f32_32x32x16_bf16 v[48:63], v[184:187], v[140:143], v[48:63]
	v_mfma_f32_32x32x16_bf16 v[32:47], v[188:191], v[140:143], v[32:47]
	v_mfma_f32_32x32x16_bf16 v[16:31], v[184:187], v[144:147], v[16:31]
	v_mfma_f32_32x32x16_bf16 v[0:15], v[188:191], v[144:147], v[0:15]
	s_waitcnt lgkmcnt(0)
	s_waitcnt vmcnt(8)
	s_barrier
	s_waitcnt lgkmcnt(0)
	v_mfma_f32_32x32x16_bf16 v[112:127], v[192:195], v[148:151], v[112:127]
	ds_read_b128 v[184:187], v131
	ds_read_b128 v[132:135], v128
	v_mfma_f32_32x32x16_bf16 v[96:111], v[208:211], v[148:151], v[96:111]
	ds_read_b128 v[188:191], v131 offset:2048
	ds_read_b128 v[136:139], v128 offset:2048
	v_mfma_f32_32x32x16_bf16 v[80:95], v[192:195], v[152:155], v[80:95]
	ds_read_b128 v[140:143], v128 offset:4096
	ds_read_b128 v[144:147], v128 offset:6144
	v_mfma_f32_32x32x16_bf16 v[64:79], v[208:211], v[152:155], v[64:79]
	v_mfma_f32_32x32x16_bf16 v[48:63], v[192:195], v[156:159], v[48:63]
	v_mfma_f32_32x32x16_bf16 v[32:47], v[208:211], v[156:159], v[32:47]
	v_mfma_f32_32x32x16_bf16 v[16:31], v[192:195], v[180:183], v[16:31]
	v_mfma_f32_32x32x16_bf16 v[0:15], v[208:211], v[180:183], v[0:15]
	s_waitcnt lgkmcnt(0)
	v_mfma_f32_32x32x16_bf16 v[112:127], v[184:187], v[132:135], v[112:127]
	ds_read_b128 v[192:195], v205
	ds_read_b128 v[148:151], v130
	v_mfma_f32_32x32x16_bf16 v[96:111], v[188:191], v[132:135], v[96:111]
	ds_read_b128 v[208:211], v205 offset:2048
	ds_read_b128 v[152:155], v130 offset:2048
	v_mfma_f32_32x32x16_bf16 v[80:95], v[184:187], v[136:139], v[80:95]
	ds_read_b128 v[156:159], v130 offset:4096
	ds_read_b128 v[180:183], v130 offset:6144
	v_mfma_f32_32x32x16_bf16 v[64:79], v[188:191], v[136:139], v[64:79]
	v_mfma_f32_32x32x16_bf16 v[48:63], v[184:187], v[140:143], v[48:63]
	v_mfma_f32_32x32x16_bf16 v[32:47], v[188:191], v[140:143], v[32:47]
	v_mfma_f32_32x32x16_bf16 v[16:31], v[184:187], v[144:147], v[16:31]
	v_mfma_f32_32x32x16_bf16 v[0:15], v[188:191], v[144:147], v[0:15]
	s_waitcnt lgkmcnt(0)
	s_waitcnt vmcnt(4)
	s_barrier
; template <class AL, class BL, class EP>
; DI void gemm_tile256(AL al, BL bl, EP ep, int K, char* smem) {
;     ...
;   for (int kt = 0; kt < KT; kt += 2) {
;     G_STEP(0, kt);
;     if (kt + 1 >= KT) break;
;     G_STEP(1, kt + 1);
;   }
	s_waitcnt lgkmcnt(0)
	v_mfma_f32_32x32x16_bf16 v[112:127], v[192:195], v[148:151], v[112:127]
	ds_read_b128 v[184:187], v131 offset:32768
	ds_read_b128 v[132:135], v128 offset:32768
	v_mfma_f32_32x32x16_bf16 v[96:111], v[208:211], v[148:151], v[96:111]
	ds_read_b128 v[188:191], v131 offset:34816
	ds_read_b128 v[136:139], v128 offset:34816
	v_mfma_f32_32x32x16_bf16 v[80:95], v[192:195], v[152:155], v[80:95]
	ds_read_b128 v[140:143], v128 offset:36864
	ds_read_b128 v[144:147], v128 offset:38912
	v_mfma_f32_32x32x16_bf16 v[64:79], v[208:211], v[152:155], v[64:79]
	v_mfma_f32_32x32x16_bf16 v[48:63], v[192:195], v[156:159], v[48:63]
	v_mfma_f32_32x32x16_bf16 v[32:47], v[208:211], v[156:159], v[32:47]
	v_mfma_f32_32x32x16_bf16 v[16:31], v[192:195], v[180:183], v[16:31]
	v_mfma_f32_32x32x16_bf16 v[0:15], v[208:211], v[180:183], v[0:15]
	s_waitcnt lgkmcnt(0)
	v_mfma_f32_32x32x16_bf16 v[112:127], v[184:187], v[132:135], v[112:127]
	ds_read_b128 v[192:195], v205 offset:32768
	ds_read_b128 v[148:151], v130 offset:32768
	v_mfma_f32_32x32x16_bf16 v[96:111], v[188:191], v[132:135], v[96:111]
	ds_read_b128 v[208:211], v205 offset:34816
	ds_read_b128 v[152:155], v130 offset:34816
	v_mfma_f32_32x32x16_bf16 v[80:95], v[184:187], v[136:139], v[80:95]
	ds_read_b128 v[156:159], v130 offset:36864
	ds_read_b128 v[180:183], v130 offset:38912
	v_mfma_f32_32x32x16_bf16 v[64:79], v[188:191], v[136:139], v[64:79]
	v_mfma_f32_32x32x16_bf16 v[48:63], v[184:187], v[140:143], v[48:63]
	v_mfma_f32_32x32x16_bf16 v[32:47], v[188:191], v[140:143], v[32:47]
	v_mfma_f32_32x32x16_bf16 v[16:31], v[184:187], v[144:147], v[16:31]
	v_mfma_f32_32x32x16_bf16 v[0:15], v[188:191], v[144:147], v[0:15]
	s_waitcnt lgkmcnt(0)
	s_waitcnt vmcnt(0)
	s_barrier
	s_waitcnt lgkmcnt(0)
	v_mfma_f32_32x32x16_bf16 v[112:127], v[192:195], v[148:151], v[112:127]
	ds_read_b128 v[184:187], v212
	ds_read_b128 v[132:135], v206
	v_mfma_f32_32x32x16_bf16 v[96:111], v[208:211], v[148:151], v[96:111]
	ds_read_b128 v[188:191], v212 offset:2048
	ds_read_b128 v[136:139], v206 offset:2048
	v_mfma_f32_32x32x16_bf16 v[80:95], v[192:195], v[152:155], v[80:95]
	ds_read_b128 v[140:143], v206 offset:4096
	ds_read_b128 v[144:147], v206 offset:6144
	v_mfma_f32_32x32x16_bf16 v[64:79], v[208:211], v[152:155], v[64:79]
	v_mfma_f32_32x32x16_bf16 v[48:63], v[192:195], v[156:159], v[48:63]
	v_mfma_f32_32x32x16_bf16 v[32:47], v[208:211], v[156:159], v[32:47]
	v_mfma_f32_32x32x16_bf16 v[16:31], v[192:195], v[180:183], v[16:31]
	v_mfma_f32_32x32x16_bf16 v[0:15], v[208:211], v[180:183], v[0:15]
	s_waitcnt lgkmcnt(0)
	v_mfma_f32_32x32x16_bf16 v[112:127], v[184:187], v[132:135], v[112:127]
	ds_read_b128 v[192:195], v213
	ds_read_b128 v[148:151], v207
	v_mfma_f32_32x32x16_bf16 v[96:111], v[188:191], v[132:135], v[96:111]
	ds_read_b128 v[208:211], v213 offset:2048
	ds_read_b128 v[152:155], v207 offset:2048
	v_mfma_f32_32x32x16_bf16 v[80:95], v[184:187], v[136:139], v[80:95]
	ds_read_b128 v[156:159], v207 offset:4096
	ds_read_b128 v[180:183], v207 offset:6144
	v_mfma_f32_32x32x16_bf16 v[64:79], v[188:191], v[136:139], v[64:79]
	v_mfma_f32_32x32x16_bf16 v[48:63], v[184:187], v[140:143], v[48:63]
	v_mfma_f32_32x32x16_bf16 v[32:47], v[188:191], v[140:143], v[32:47]
	v_mfma_f32_32x32x16_bf16 v[16:31], v[184:187], v[144:147], v[16:31]
	v_mfma_f32_32x32x16_bf16 v[0:15], v[188:191], v[144:147], v[0:15]
	s_waitcnt lgkmcnt(0)
	s_waitcnt lgkmcnt(0)
	v_mfma_f32_32x32x16_bf16 v[112:127], v[192:195], v[148:151], v[112:127]
	v_mfma_f32_32x32x16_bf16 v[96:111], v[208:211], v[148:151], v[96:111]
	v_mfma_f32_32x32x16_bf16 v[80:95], v[192:195], v[152:155], v[80:95]
	v_mfma_f32_32x32x16_bf16 v[64:79], v[208:211], v[152:155], v[64:79]
	v_mfma_f32_32x32x16_bf16 v[48:63], v[192:195], v[156:159], v[48:63]
	v_mfma_f32_32x32x16_bf16 v[32:47], v[208:211], v[156:159], v[32:47]
	v_mfma_f32_32x32x16_bf16 v[16:31], v[192:195], v[180:183], v[16:31]
	v_mfma_f32_32x32x16_bf16 v[0:15], v[208:211], v[180:183], v[0:15]
	s_nop 15
	s_nop 3
	s_branch .LBB0_666

; DI int tid512() { int t = threadIdx_x_raw(); asm volatile("" : "+v"(t)); return t; }
; #define G_LOADA(kt_) { _Pragma("unroll") for (int i = 0; i < 4; ++i) ra[i] = al(lrow + 64 * i, (kt_) * 64 + lck * 8); }
; #define G_LOADB(kt_) { _Pragma("unroll") for (int i = 0; i < 4; ++i) rb[i] = bl(lrow + 64 * i, (kt_) * 64 + lck * 8); }
; #define G_STOREA(buf_) { bf16_t* nA = sA + (buf_) * 256 * GLD; _Pragma("unroll") for (int i = 0; i < 4; ++i) *(u32x4*)(nA + (lrow + 64 * i) * GLD + lck * 8) = ra[i]; }
; #define G_STOREB(buf_) { bf16_t* nB = sB + (buf_) * 256 * GLD; _Pragma("unroll") for (int i = 0; i < 4; ++i) *(u32x4*)(nB + (lrow + 64 * i) * GLD + lck * 8) = rb[i]; }
; template <class AL, class BL, class EP>
; DI void gemm_tile256(AL al, BL bl, EP ep, int K, char* smem) {
;   bf16_t* sA = (bf16_t*)smem;
;   bf16_t* sB = sA + 2 * 256 * GLD;
;   const int tid = tid512(), lane = tid & 63, w = tid >> 6, wm = w >> 2, wn = w & 3, r = lane & 31, h = lane >> 5;
;   const int lrow = tid >> 3, lck = tid & 7;
;   f32x16 acc[4][2];
; #pragma unroll
;   for (int i = 0; i < 4; ++i)
; #pragma unroll
;     for (int j = 0; j < 2; ++j)
; #pragma unroll
;       for (int q = 0; q < 16; ++q) acc[i][j][q] = 0.f;
;   u32x4 ra[4], rb[4];
;   const int KT = K >> 6;
;     ...
;   G_LOADA(0); G_LOADB(0);
;   __syncthreads();
;   G_STOREA(0); G_STOREB(0);
;   if (KT > 1) G_LOADB(1);
;   __syncthreads();
;   DI u32x4 operator()(int r, int k) const {
;     int row = row0 + r;
;     row = row < nrows ? row : nrows - 1;
;     return ldg16(base + (size_t)row * ld + k);
;   }
.LBB0_1255:
	s_cmp_lg_u32 s10, 1
	s_mov_b64 s[0:1], -1
	s_cbranch_scc0 .LBB0_1274
	v_mov_b32_e32 v42, v196
	v_readlane_b32 s40, v246, 17
	v_ashrrev_i32_e32 v43, 3, v42
	v_lshlrev_b32_e32 v0, 4, v42
	v_add_u32_e32 v14, s22, v43
	v_and_b32_e32 v160, 0x70, v0
	v_lshl_add_u64 v[8:9], s[72:73], 0, v[160:161]
	v_min_i32_e32 v44, 0x7fff, v14
	v_add_u32_e32 v0, 64, v14
	v_mad_i64_i32 v[10:11], s[0:1], v44, s13, v[8:9]
	v_min_i32_e32 v45, 0x7fff, v0
	v_mad_i64_i32 v[12:13], s[0:1], v45, s13, v[8:9]
	v_mov_b32_e32 v254, v10
	v_mov_b32_e32 v255, v11
	v_add_u32_e32 v10, 0x80, v14
	v_min_i32_e32 v46, 0x7fff, v10
	v_add_u32_e32 v10, 0xc0, v14
	v_add_u32_e32 v26, s21, v43
	v_mad_i64_i32 v[16:17], s[0:1], v46, s13, v[8:9]
	v_min_i32_e32 v47, 0x7fff, v10
	v_add_u32_e32 v27, 0x80, v26
	v_mad_i64_i32 v[18:19], s[0:1], v47, s13, v[8:9]
	v_lshl_add_u64 v[24:25], s[2:3], 0, v[160:161]
	v_min_i32_e32 v48, 0x3ff, v26
	v_add_u32_e32 v16, 64, v26
	v_min_i32_e32 v50, 0x3ff, v27
	v_add_u32_e32 v26, 0xc0, v26
	v_mad_i64_i32 v[32:33], s[0:1], v48, s13, v[24:25]
	v_min_i32_e32 v49, 0x3ff, v16
	v_mad_i64_i32 v[36:37], s[0:1], v50, s13, v[24:25]
	v_min_i32_e32 v51, 0x3ff, v26
	v_mad_i64_i32 v[34:35], s[0:1], v49, s13, v[24:25]
	v_mov_b32_e32 v252, v32
	v_mov_b32_e32 v253, v33
	v_mad_i64_i32 v[38:39], s[0:1], v51, s13, v[24:25]
	v_bfe_u32 v198, v42, 6, 2
	v_and_b32_e32 v52, 31, v42
	v_ashrrev_i32_e32 v53, 1, v42
	v_lshrrev_b32_e32 v42, 2, v42
	v_mul_lo_u32 v43, v43, s14
	v_and_or_b32 v199, v53, s15, v52
	v_and_b32_e32 v200, 8, v42
	v_lshl_or_b32 v52, v198, 6, v52
	v_readlane_b32 s54, v246, 31
	v_readlane_b32 s55, v246, 32
	v_add_u32_e32 v201, v160, v43
	v_or_b32_e32 v53, 0x12000, v160
	v_lshlrev_b32_e32 v42, 1, v200
	v_mul_u32_u24_e32 v52, 0x48, v52
	v_mov_b64_e32 v[40:41], s[54:55]
	v_or_b32_e32 v54, 0x1b000, v160
	v_add_u32_e32 v202, v53, v43
	v_mad_u64_u32 v[162:163], s[0:1], v199, s14, v[42:43]
	v_lshl_add_u32 v42, v52, 1, v42
	v_mad_i64_i32 v[164:165], s[0:1], v48, s13, v[40:41]
	v_add_u32_e32 v163, 0x12000, v42
	v_add_u32_e32 v203, 0x1b000, v42
	v_mad_i64_i32 v[166:167], s[0:1], v49, s13, v[40:41]
	v_mad_i64_i32 v[168:169], s[0:1], v50, s13, v[40:41]
	v_mad_i64_i32 v[170:171], s[0:1], v51, s13, v[40:41]
	v_mad_i64_i32 v[172:173], s[0:1], v44, s13, v[40:41]
	v_mad_i64_i32 v[174:175], s[0:1], v45, s13, v[40:41]
	v_mad_i64_i32 v[176:177], s[0:1], v46, s13, v[40:41]
	v_mad_i64_i32 v[178:179], s[0:1], v47, s13, v[40:41]
	s_mov_b32 s23, 0
	v_add_u32_e32 v204, v54, v43
	v_readlane_b32 s41, v246, 18
	v_readlane_b32 s42, v246, 19
	v_readlane_b32 s43, v246, 20
	v_readlane_b32 s44, v246, 21
	v_readlane_b32 s45, v246, 22
	v_readlane_b32 s46, v246, 23
	v_readlane_b32 s47, v246, 24
	v_readlane_b32 s48, v246, 25
	v_readlane_b32 s49, v246, 26
	v_readlane_b32 s50, v246, 27
	v_readlane_b32 s51, v246, 28
	v_readlane_b32 s52, v246, 29
	v_readlane_b32 s53, v246, 30
	v_lshrrev_b32_e32 v228, 6, v196
	s_mov_b32 s6, 64
	v_readfirstlane_b32 s26, v228
	s_mov_b32 s7, 0
	s_mov_b32 s10, 0xb0000
	s_mov_b32 s11, 0
	v_bfe_u32 v226, v196, 2, 4
	s_lshl_b32 s27, s26, 3
	v_add_u32_e32 v226, s27, v226
	s_mov_b32 s27, 0x1600
	v_mul_lo_u32 v226, v226, s27
	v_bfe_u32 v228, v196, 4, 2
	v_and_b32_e32 v227, 3, v196
	v_xor_b32_e32 v228, v227, v228
	v_lshl_add_u32 v226, v228, 4, v226
	v_mov_b32_e32 v227, 0
	v_readlane_b32 s24, v254, 0
	v_readlane_b32 s25, v255, 0
	s_nop 1
	v_lshl_add_u64 v[218:219], s[24:25], 0, v[226:227]
	v_lshl_add_u64 v[220:221], v[218:219], 0, s[10:11]
	v_readlane_b32 s24, v252, 0
	v_readlane_b32 s25, v253, 0
	s_nop 1
	v_lshl_add_u64 v[222:223], s[24:25], 0, v[226:227]
	v_lshl_add_u64 v[224:225], v[222:223], 0, s[10:11]
	v_and_b32_e32 v226, 31, v196
	v_bfe_u32 v228, v196, 2, 2
	v_bfe_u32 v227, v196, 5, 1
	v_xor_b32_e32 v228, v227, v228
	v_lshlrev_b32_e32 v228, 4, v228
	v_lshl_or_b32 v226, v226, 6, v228
	s_lshr_b32 s27, s26, 2
	s_lshl_b32 s27, s27, 13
	v_add_u32_e32 v128, s27, v226
	s_and_b32 s27, s26, 3
	s_lshl_b32 s27, s27, 12
	s_add_u32 s27, s27, 0x4000
	v_add_u32_e32 v131, s27, v226
	v_xor_b32_e32 v130, 0x20, v128
	v_xor_b32_e32 v205, 0x20, v131
	v_add_u32_e32 v206, 0x10000, v128
	v_add_u32_e32 v212, 0x10000, v131
	v_add_u32_e32 v214, 0x20000, v128
	v_add_u32_e32 v216, 0x20000, v131
	v_add_u32_e32 v207, 0x10000, v130
	v_add_u32_e32 v213, 0x10000, v205
	v_add_u32_e32 v215, 0x20000, v130
	v_add_u32_e32 v217, 0x20000, v205
	s_lshl_b32 s26, s26, 10
	s_waitcnt lgkmcnt(0)
	s_barrier
; #define G_LOADA(kt_) { _Pragma("unroll") for (int i = 0; i < 4; ++i) ra[i] = al(lrow + 64 * i, (kt_) * 64 + lck * 8); }
; #define G_LOADB(kt_) { _Pragma("unroll") for (int i = 0; i < 4; ++i) rb[i] = bl(lrow + 64 * i, (kt_) * 64 + lck * 8); }
; #define G_STOREA(buf_) { bf16_t* nA = sA + (buf_) * 256 * GLD; _Pragma("unroll") for (int i = 0; i < 4; ++i) *(u32x4*)(nA + (lrow + 64 * i) * GLD + lck * 8) = ra[i]; }
; #define G_STOREB(buf_) { bf16_t* nB = sB + (buf_) * 256 * GLD; _Pragma("unroll") for (int i = 0; i < 4; ++i) *(u32x4*)(nB + (lrow + 64 * i) * GLD + lck * 8) = rb[i]; }
; template <class AL, class BL, class EP>
; DI void gemm_tile256(AL al, BL bl, EP ep, int K, char* smem) {
;     ...
;   f32x16 acc[4][2];
; #pragma unroll
;   for (int i = 0; i < 4; ++i)
; #pragma unroll
;     for (int j = 0; j < 2; ++j)
; #pragma unroll
;       for (int q = 0; q < 16; ++q) acc[i][j][q] = 0.f;
;     ...
;   G_LOADA(0); G_LOADB(0);
;   __syncthreads();
;   G_STOREA(0); G_STOREB(0);
;   if (KT > 1) G_LOADB(1);
;   __syncthreads();
	s_add_u32 m0, s26, 0x0
	s_nop 0
	global_load_lds_dwordx4 v[218:219], off
	v_lshl_add_u64 v[218:219], v[218:219], 0, s[6:7]
	s_add_u32 m0, s26, 0x4000
	s_nop 0
	global_load_lds_dwordx4 v[222:223], off
	v_lshl_add_u64 v[222:223], v[222:223], 0, s[6:7]
	s_add_u32 m0, s26, 0x2000
	s_nop 0
	global_load_lds_dwordx4 v[220:221], off
	v_lshl_add_u64 v[220:221], v[220:221], 0, s[6:7]
	s_add_u32 m0, s26, 0x6000
	s_nop 0
	global_load_lds_dwordx4 v[224:225], off
	v_lshl_add_u64 v[224:225], v[224:225], 0, s[6:7]
	s_add_u32 m0, s26, 0x8000
	s_nop 0
	global_load_lds_dwordx4 v[218:219], off
	v_lshl_add_u64 v[218:219], v[218:219], 0, s[6:7]
	s_add_u32 m0, s26, 0xc000
	s_nop 0
	global_load_lds_dwordx4 v[222:223], off
	v_lshl_add_u64 v[222:223], v[222:223], 0, s[6:7]
	s_add_u32 m0, s26, 0xa000
	s_nop 0
	global_load_lds_dwordx4 v[220:221], off
	v_lshl_add_u64 v[220:221], v[220:221], 0, s[6:7]
	s_add_u32 m0, s26, 0xe000
	s_nop 0
	global_load_lds_dwordx4 v[224:225], off
	v_lshl_add_u64 v[224:225], v[224:225], 0, s[6:7]
	s_add_u32 m0, s26, 0x10000
	s_nop 0
	global_load_lds_dwordx4 v[218:219], off
	v_lshl_add_u64 v[218:219], v[218:219], 0, s[6:7]
	s_add_u32 m0, s26, 0x14000
	s_nop 0
	global_load_lds_dwordx4 v[222:223], off
	v_lshl_add_u64 v[222:223], v[222:223], 0, s[6:7]
	s_add_u32 m0, s26, 0x12000
	s_nop 0
	global_load_lds_dwordx4 v[220:221], off
	v_lshl_add_u64 v[220:221], v[220:221], 0, s[6:7]
	s_add_u32 m0, s26, 0x16000
	s_nop 0
	global_load_lds_dwordx4 v[224:225], off
	v_lshl_add_u64 v[224:225], v[224:225], 0, s[6:7]
	s_add_u32 m0, s26, 0x18000
	s_nop 0
	global_load_lds_dwordx4 v[218:219], off
	v_lshl_add_u64 v[218:219], v[218:219], 0, s[6:7]
	s_add_u32 m0, s26, 0x1c000
	s_nop 0
	global_load_lds_dwordx4 v[222:223], off
	v_lshl_add_u64 v[222:223], v[222:223], 0, s[6:7]
	s_add_u32 m0, s26, 0x1a000
	s_nop 0
	global_load_lds_dwordx4 v[220:221], off
	v_lshl_add_u64 v[220:221], v[220:221], 0, s[6:7]
	s_add_u32 m0, s26, 0x1e000
	s_nop 0
	global_load_lds_dwordx4 v[224:225], off
	v_lshl_add_u64 v[224:225], v[224:225], 0, s[6:7]
	s_add_u32 m0, s26, 0x20000
	s_nop 0
	global_load_lds_dwordx4 v[218:219], off
	v_lshl_add_u64 v[218:219], v[218:219], 0, s[6:7]
	s_add_u32 m0, s26, 0x24000
	s_nop 0
	global_load_lds_dwordx4 v[222:223], off
	v_lshl_add_u64 v[222:223], v[222:223], 0, s[6:7]
	v_mov_b64_e32 v[112:113], 0
	v_mov_b64_e32 v[114:115], 0
	v_mov_b64_e32 v[116:117], 0
	v_mov_b64_e32 v[118:119], 0
	v_mov_b64_e32 v[120:121], 0
	v_mov_b64_e32 v[122:123], 0
	v_mov_b64_e32 v[124:125], 0
	v_mov_b64_e32 v[126:127], 0
	v_mov_b64_e32 v[96:97], 0
	v_mov_b64_e32 v[98:99], 0
	v_mov_b64_e32 v[100:101], 0
	v_mov_b64_e32 v[102:103], 0
	v_mov_b64_e32 v[104:105], 0
	v_mov_b64_e32 v[106:107], 0
	v_mov_b64_e32 v[108:109], 0
	v_mov_b64_e32 v[110:111], 0
	v_mov_b64_e32 v[80:81], 0
	v_mov_b64_e32 v[82:83], 0
	v_mov_b64_e32 v[84:85], 0
	v_mov_b64_e32 v[86:87], 0
	v_mov_b64_e32 v[88:89], 0
	v_mov_b64_e32 v[90:91], 0
	v_mov_b64_e32 v[92:93], 0
	v_mov_b64_e32 v[94:95], 0
	v_mov_b64_e32 v[64:65], 0
	v_mov_b64_e32 v[66:67], 0
	v_mov_b64_e32 v[68:69], 0
	v_mov_b64_e32 v[70:71], 0
	v_mov_b64_e32 v[72:73], 0
	v_mov_b64_e32 v[74:75], 0
	v_mov_b64_e32 v[76:77], 0
	v_mov_b64_e32 v[78:79], 0
	v_mov_b64_e32 v[48:49], 0
	v_mov_b64_e32 v[50:51], 0
	v_mov_b64_e32 v[52:53], 0
	v_mov_b64_e32 v[54:55], 0
	v_mov_b64_e32 v[56:57], 0
	v_mov_b64_e32 v[58:59], 0
	v_mov_b64_e32 v[60:61], 0
	v_mov_b64_e32 v[62:63], 0
	v_mov_b64_e32 v[32:33], 0
	v_mov_b64_e32 v[34:35], 0
	v_mov_b64_e32 v[36:37], 0
	v_mov_b64_e32 v[38:39], 0
	v_mov_b64_e32 v[40:41], 0
	v_mov_b64_e32 v[42:43], 0
	v_mov_b64_e32 v[44:45], 0
	v_mov_b64_e32 v[46:47], 0
	v_mov_b64_e32 v[16:17], 0
	v_mov_b64_e32 v[18:19], 0
	v_mov_b64_e32 v[20:21], 0
	v_mov_b64_e32 v[22:23], 0
	v_mov_b64_e32 v[24:25], 0
	v_mov_b64_e32 v[26:27], 0
	v_mov_b64_e32 v[28:29], 0
	v_mov_b64_e32 v[30:31], 0
	v_mov_b64_e32 v[0:1], 0
	v_mov_b64_e32 v[2:3], 0
	v_mov_b64_e32 v[4:5], 0
	v_mov_b64_e32 v[6:7], 0
	v_mov_b64_e32 v[8:9], 0
	v_mov_b64_e32 v[10:11], 0
	v_mov_b64_e32 v[12:13], 0
	v_mov_b64_e32 v[14:15], 0
	s_mov_b32 s27, 16
	s_waitcnt vmcnt(14)
	s_barrier
	ds_read_b128 v[184:187], v131
	ds_read_b128 v[132:135], v128
	ds_read_b128 v[188:191], v131 offset:2048
	ds_read_b128 v[136:139], v128 offset:2048
	ds_read_b128 v[140:143], v128 offset:4096
	ds_read_b128 v[144:147], v128 offset:6144
; template <class AL, class BL, class EP>
; DI void gemm_tile256(AL al, BL bl, EP ep, int K, char* smem) {
;     ...
;   for (int kt = 0; kt < KT; kt += 2) {
;     G_STEP(0, kt);
;     if (kt + 1 >= KT) break;
;     G_STEP(1, kt + 1);
;   }
.Lgk_ph16_loop:
	s_waitcnt lgkmcnt(0)
	v_mfma_f32_32x32x16_bf16 v[112:127], v[184:187], v[132:135], v[112:127]
	ds_read_b128 v[192:195], v205
	ds_read_b128 v[148:151], v130
	v_mfma_f32_32x32x16_bf16 v[96:111], v[188:191], v[132:135], v[96:111]
	ds_read_b128 v[208:211], v205 offset:2048
	ds_read_b128 v[152:155], v130 offset:2048
	v_mfma_f32_32x32x16_bf16 v[80:95], v[184:187], v[136:139], v[80:95]
	ds_read_b128 v[156:159], v130 offset:4096
	ds_read_b128 v[180:183], v130 offset:6144
	v_mfma_f32_32x32x16_bf16 v[64:79], v[188:191], v[136:139], v[64:79]
	s_add_u32 m0, s26, 0x22000
	s_nop 0
	global_load_lds_dwordx4 v[220:221], off
	v_lshl_add_u64 v[220:221], v[220:221], 0, s[6:7]
	v_mfma_f32_32x32x16_bf16 v[48:63], v[184:187], v[140:143], v[48:63]
	v_mfma_f32_32x32x16_bf16 v[32:47], v[188:191], v[140:143], v[32:47]
	v_mfma_f32_32x32x16_bf16 v[16:31], v[184:187], v[144:147], v[16:31]
	v_mfma_f32_32x32x16_bf16 v[0:15], v[188:191], v[144:147], v[0:15]
	s_add_u32 m0, s26, 0x26000
	s_nop 0
	global_load_lds_dwordx4 v[224:225], off
	v_lshl_add_u64 v[224:225], v[224:225], 0, s[6:7]
	s_waitcnt lgkmcnt(0)
	s_waitcnt vmcnt(12)
	s_barrier
	s_waitcnt lgkmcnt(0)
	v_mfma_f32_32x32x16_bf16 v[112:127], v[192:195], v[148:151], v[112:127]
	ds_read_b128 v[184:187], v131 offset:32768
	ds_read_b128 v[132:135], v128 offset:32768
	v_mfma_f32_32x32x16_bf16 v[96:111], v[208:211], v[148:151], v[96:111]
	ds_read_b128 v[188:191], v131 offset:34816
	ds_read_b128 v[136:139], v128 offset:34816
	v_mfma_f32_32x32x16_bf16 v[80:95], v[192:195], v[152:155], v[80:95]
	ds_read_b128 v[140:143], v128 offset:36864
	ds_read_b128 v[144:147], v128 offset:38912
	v_mfma_f32_32x32x16_bf16 v[64:79], v[208:211], v[152:155], v[64:79]
	s_add_u32 m0, s26, 0x0
	s_nop 0
	global_load_lds_dwordx4 v[218:219], off
	v_lshl_add_u64 v[218:219], v[218:219], 0, s[6:7]
	v_mfma_f32_32x32x16_bf16 v[48:63], v[192:195], v[156:159], v[48:63]
	v_mfma_f32_32x32x16_bf16 v[32:47], v[208:211], v[156:159], v[32:47]
	v_mfma_f32_32x32x16_bf16 v[16:31], v[192:195], v[180:183], v[16:31]
	v_mfma_f32_32x32x16_bf16 v[0:15], v[208:211], v[180:183], v[0:15]
	s_add_u32 m0, s26, 0x4000
	s_nop 0
	global_load_lds_dwordx4 v[222:223], off
	v_lshl_add_u64 v[222:223], v[222:223], 0, s[6:7]
	s_waitcnt lgkmcnt(0)
	v_mfma_f32_32x32x16_bf16 v[112:127], v[184:187], v[132:135], v[112:127]
	ds_read_b128 v[192:195], v205 offset:32768
	ds_read_b128 v[148:151], v130 offset:32768
	v_mfma_f32_32x32x16_bf16 v[96:111], v[188:191], v[132:135], v[96:111]
	ds_read_b128 v[208:211], v205 offset:34816
	ds_read_b128 v[152:155], v130 offset:34816
	v_mfma_f32_32x32x16_bf16 v[80:95], v[184:187], v[136:139], v[80:95]
	ds_read_b128 v[156:159], v130 offset:36864
	ds_read_b128 v[180:183], v130 offset:38912
	v_mfma_f32_32x32x16_bf16 v[64:79], v[188:191], v[136:139], v[64:79]
	s_add_u32 m0, s26, 0x2000
	s_nop 0
	global_load_lds_dwordx4 v[220:221], off
	v_lshl_add_u64 v[220:221], v[220:221], 0, s[6:7]
	v_mfma_f32_32x32x16_bf16 v[48:63], v[184:187], v[140:143], v[48:63]
	v_mfma_f32_32x32x16_bf16 v[32:47], v[188:191], v[140:143], v[32:47]
	v_mfma_f32_32x32x16_bf16 v[16:31], v[184:187], v[144:147], v[16:31]
	v_mfma_f32_32x32x16_bf16 v[0:15], v[188:191], v[144:147], v[0:15]
	s_add_u32 m0, s26, 0x6000
	s_nop 0
	global_load_lds_dwordx4 v[224:225], off
	v_lshl_add_u64 v[224:225], v[224:225], 0, s[6:7]
	s_waitcnt lgkmcnt(0)
	s_waitcnt vmcnt(12)
	s_barrier
	s_waitcnt lgkmcnt(0)
	v_mfma_f32_32x32x16_bf16 v[112:127], v[192:195], v[148:151], v[112:127]
	ds_read_b128 v[184:187], v212
	ds_read_b128 v[132:135], v206
	v_mfma_f32_32x32x16_bf16 v[96:111], v[208:211], v[148:151], v[96:111]
	ds_read_b128 v[188:191], v212 offset:2048
	ds_read_b128 v[136:139], v206 offset:2048
	v_mfma_f32_32x32x16_bf16 v[80:95], v[192:195], v[152:155], v[80:95]
	ds_read_b128 v[140:143], v206 offset:4096
	ds_read_b128 v[144:147], v206 offset:6144
	v_mfma_f32_32x32x16_bf16 v[64:79], v[208:211], v[152:155], v[64:79]
	s_add_u32 m0, s26, 0x8000
	s_nop 0
	global_load_lds_dwordx4 v[218:219], off
	v_lshl_add_u64 v[218:219], v[218:219], 0, s[6:7]
	v_mfma_f32_32x32x16_bf16 v[48:63], v[192:195], v[156:159], v[48:63]
	v_mfma_f32_32x32x16_bf16 v[32:47], v[208:211], v[156:159], v[32:47]
	v_mfma_f32_32x32x16_bf16 v[16:31], v[192:195], v[180:183], v[16:31]
	v_mfma_f32_32x32x16_bf16 v[0:15], v[208:211], v[180:183], v[0:15]
	s_add_u32 m0, s26, 0xc000
	s_nop 0
	global_load_lds_dwordx4 v[222:223], off
	v_lshl_add_u64 v[222:223], v[222:223], 0, s[6:7]
	s_waitcnt lgkmcnt(0)
	v_mfma_f32_32x32x16_bf16 v[112:127], v[184:187], v[132:135], v[112:127]
	ds_read_b128 v[192:195], v213
	ds_read_b128 v[148:151], v207
	v_mfma_f32_32x32x16_bf16 v[96:111], v[188:191], v[132:135], v[96:111]
	ds_read_b128 v[208:211], v213 offset:2048
	ds_read_b128 v[152:155], v207 offset:2048
	v_mfma_f32_32x32x16_bf16 v[80:95], v[184:187], v[136:139], v[80:95]
	ds_read_b128 v[156:159], v207 offset:4096
	ds_read_b128 v[180:183], v207 offset:6144
	v_mfma_f32_32x32x16_bf16 v[64:79], v[188:191], v[136:139], v[64:79]
	s_add_u32 m0, s26, 0xa000
	s_nop 0
	global_load_lds_dwordx4 v[220:221], off
	v_lshl_add_u64 v[220:221], v[220:221], 0, s[6:7]
	v_mfma_f32_32x32x16_bf16 v[48:63], v[184:187], v[140:143], v[48:63]
	v_mfma_f32_32x32x16_bf16 v[32:47], v[188:191], v[140:143], v[32:47]
	v_mfma_f32_32x32x16_bf16 v[16:31], v[184:187], v[144:147], v[16:31]
	v_mfma_f32_32x32x16_bf16 v[0:15], v[188:191], v[144:147], v[0:15]
	s_add_u32 m0, s26, 0xe000
	s_nop 0
	global_load_lds_dwordx4 v[224:225], off
	v_lshl_add_u64 v[224:225], v[224:225], 0, s[6:7]
	s_waitcnt lgkmcnt(0)
	s_waitcnt vmcnt(12)
	s_barrier
; template <class AL, class BL, class EP>
; DI void gemm_tile256(AL al, BL bl, EP ep, int K, char* smem) {
;     ...
;   for (int kt = 0; kt < KT; kt += 2) {
;     G_STEP(0, kt);
;     if (kt + 1 >= KT) break;
;     G_STEP(1, kt + 1);
;   }
	s_waitcnt lgkmcnt(0)
	v_mfma_f32_32x32x16_bf16 v[112:127], v[192:195], v[148:151], v[112:127]
	ds_read_b128 v[184:187], v212 offset:32768
	ds_read_b128 v[132:135], v206 offset:32768
	v_mfma_f32_32x32x16_bf16 v[96:111], v[208:211], v[148:151], v[96:111]
	ds_read_b128 v[188:191], v212 offset:34816
	ds_read_b128 v[136:139], v206 offset:34816
	v_mfma_f32_32x32x16_bf16 v[80:95], v[192:195], v[152:155], v[80:95]
	ds_read_b128 v[140:143], v206 offset:36864
	ds_read_b128 v[144:147], v206 offset:38912
	v_mfma_f32_32x32x16_bf16 v[64:79], v[208:211], v[152:155], v[64:79]
	s_add_u32 m0, s26, 0x10000
	s_nop 0
	global_load_lds_dwordx4 v[218:219], off
	v_lshl_add_u64 v[218:219], v[218:219], 0, s[6:7]
	v_mfma_f32_32x32x16_bf16 v[48:63], v[192:195], v[156:159], v[48:63]
	v_mfma_f32_32x32x16_bf16 v[32:47], v[208:211], v[156:159], v[32:47]
	v_mfma_f32_32x32x16_bf16 v[16:31], v[192:195], v[180:183], v[16:31]
	v_mfma_f32_32x32x16_bf16 v[0:15], v[208:211], v[180:183], v[0:15]
	s_add_u32 m0, s26, 0x14000
	s_nop 0
	global_load_lds_dwordx4 v[222:223], off
	v_lshl_add_u64 v[222:223], v[222:223], 0, s[6:7]
	s_waitcnt lgkmcnt(0)
	v_mfma_f32_32x32x16_bf16 v[112:127], v[184:187], v[132:135], v[112:127]
	ds_read_b128 v[192:195], v213 offset:32768
	ds_read_b128 v[148:151], v207 offset:32768
	v_mfma_f32_32x32x16_bf16 v[96:111], v[188:191], v[132:135], v[96:111]
	ds_read_b128 v[208:211], v213 offset:34816
	ds_read_b128 v[152:155], v207 offset:34816
	v_mfma_f32_32x32x16_bf16 v[80:95], v[184:187], v[136:139], v[80:95]
	ds_read_b128 v[156:159], v207 offset:36864
	ds_read_b128 v[180:183], v207 offset:38912
	v_mfma_f32_32x32x16_bf16 v[64:79], v[188:191], v[136:139], v[64:79]
	s_add_u32 m0, s26, 0x12000
	s_nop 0
	global_load_lds_dwordx4 v[220:221], off
	v_lshl_add_u64 v[220:221], v[220:221], 0, s[6:7]
	v_mfma_f32_32x32x16_bf16 v[48:63], v[184:187], v[140:143], v[48:63]
	v_mfma_f32_32x32x16_bf16 v[32:47], v[188:191], v[140:143], v[32:47]
	v_mfma_f32_32x32x16_bf16 v[16:31], v[184:187], v[144:147], v[16:31]
	v_mfma_f32_32x32x16_bf16 v[0:15], v[188:191], v[144:147], v[0:15]
	s_add_u32 m0, s26, 0x16000
	s_nop 0
	global_load_lds_dwordx4 v[224:225], off
	v_lshl_add_u64 v[224:225], v[224:225], 0, s[6:7]
	s_waitcnt lgkmcnt(0)
	s_waitcnt vmcnt(12)
	s_barrier
	s_waitcnt lgkmcnt(0)
	v_mfma_f32_32x32x16_bf16 v[112:127], v[192:195], v[148:151], v[112:127]
	ds_read_b128 v[184:187], v216
	ds_read_b128 v[132:135], v214
	v_mfma_f32_32x32x16_bf16 v[96:111], v[208:211], v[148:151], v[96:111]
	ds_read_b128 v[188:191], v216 offset:2048
	ds_read_b128 v[136:139], v214 offset:2048
	v_mfma_f32_32x32x16_bf16 v[80:95], v[192:195], v[152:155], v[80:95]
	ds_read_b128 v[140:143], v214 offset:4096
	ds_read_b128 v[144:147], v214 offset:6144
	v_mfma_f32_32x32x16_bf16 v[64:79], v[208:211], v[152:155], v[64:79]
	s_add_u32 m0, s26, 0x18000
	s_nop 0
	global_load_lds_dwordx4 v[218:219], off
	v_lshl_add_u64 v[218:219], v[218:219], 0, s[6:7]
	v_mfma_f32_32x32x16_bf16 v[48:63], v[192:195], v[156:159], v[48:63]
	v_mfma_f32_32x32x16_bf16 v[32:47], v[208:211], v[156:159], v[32:47]
	v_mfma_f32_32x32x16_bf16 v[16:31], v[192:195], v[180:183], v[16:31]
	v_mfma_f32_32x32x16_bf16 v[0:15], v[208:211], v[180:183], v[0:15]
	s_add_u32 m0, s26, 0x1c000
	s_nop 0
	global_load_lds_dwordx4 v[222:223], off
	v_lshl_add_u64 v[222:223], v[222:223], 0, s[6:7]
	s_waitcnt lgkmcnt(0)
	v_mfma_f32_32x32x16_bf16 v[112:127], v[184:187], v[132:135], v[112:127]
	ds_read_b128 v[192:195], v217
	ds_read_b128 v[148:151], v215
	v_mfma_f32_32x32x16_bf16 v[96:111], v[188:191], v[132:135], v[96:111]
	ds_read_b128 v[208:211], v217 offset:2048
	ds_read_b128 v[152:155], v215 offset:2048
	v_mfma_f32_32x32x16_bf16 v[80:95], v[184:187], v[136:139], v[80:95]
	ds_read_b128 v[156:159], v215 offset:4096
	ds_read_b128 v[180:183], v215 offset:6144
	v_mfma_f32_32x32x16_bf16 v[64:79], v[188:191], v[136:139], v[64:79]
	s_add_u32 m0, s26, 0x1a000
	s_nop 0
	global_load_lds_dwordx4 v[220:221], off
	v_lshl_add_u64 v[220:221], v[220:221], 0, s[6:7]
	v_mfma_f32_32x32x16_bf16 v[48:63], v[184:187], v[140:143], v[48:63]
	v_mfma_f32_32x32x16_bf16 v[32:47], v[188:191], v[140:143], v[32:47]
	v_mfma_f32_32x32x16_bf16 v[16:31], v[184:187], v[144:147], v[16:31]
	v_mfma_f32_32x32x16_bf16 v[0:15], v[188:191], v[144:147], v[0:15]
	s_add_u32 m0, s26, 0x1e000
	s_nop 0
	global_load_lds_dwordx4 v[224:225], off
	v_lshl_add_u64 v[224:225], v[224:225], 0, s[6:7]
	s_waitcnt lgkmcnt(0)
	s_waitcnt vmcnt(12)
	s_barrier
	s_waitcnt lgkmcnt(0)
	v_mfma_f32_32x32x16_bf16 v[112:127], v[192:195], v[148:151], v[112:127]
	ds_read_b128 v[184:187], v131
	ds_read_b128 v[132:135], v128
	v_mfma_f32_32x32x16_bf16 v[96:111], v[208:211], v[148:151], v[96:111]
	ds_read_b128 v[188:191], v131 offset:2048
	ds_read_b128 v[136:139], v128 offset:2048
	v_mfma_f32_32x32x16_bf16 v[80:95], v[192:195], v[152:155], v[80:95]
	ds_read_b128 v[140:143], v128 offset:4096
	ds_read_b128 v[144:147], v128 offset:6144
	v_mfma_f32_32x32x16_bf16 v[64:79], v[208:211], v[152:155], v[64:79]
	s_add_u32 m0, s26, 0x20000
	s_nop 0
	global_load_lds_dwordx4 v[218:219], off
	v_lshl_add_u64 v[218:219], v[218:219], 0, s[6:7]
	v_mfma_f32_32x32x16_bf16 v[48:63], v[192:195], v[156:159], v[48:63]
	v_mfma_f32_32x32x16_bf16 v[32:47], v[208:211], v[156:159], v[32:47]
	v_mfma_f32_32x32x16_bf16 v[16:31], v[192:195], v[180:183], v[16:31]
	v_mfma_f32_32x32x16_bf16 v[0:15], v[208:211], v[180:183], v[0:15]
	s_add_u32 m0, s26, 0x24000
	s_nop 0
	global_load_lds_dwordx4 v[222:223], off
	v_lshl_add_u64 v[222:223], v[222:223], 0, s[6:7]
	s_sub_u32 s27, s27, 1
	s_cmp_lg_u32 s27, 0
	s_cbranch_scc1 .Lgk_ph16_loop
; template <class AL, class BL, class EP>
; DI void gemm_tile256(AL al, BL bl, EP ep, int K, char* smem) {
;     ...
;   for (int kt = 0; kt < KT; kt += 2) {
;     G_STEP(0, kt);
;     if (kt + 1 >= KT) break;
;     G_STEP(1, kt + 1);
;   }
	s_waitcnt lgkmcnt(0)
	v_mfma_f32_32x32x16_bf16 v[112:127], v[184:187], v[132:135], v[112:127]
	ds_read_b128 v[192:195], v205
	ds_read_b128 v[148:151], v130
	v_mfma_f32_32x32x16_bf16 v[96:111], v[188:191], v[132:135], v[96:111]
	ds_read_b128 v[208:211], v205 offset:2048
	ds_read_b128 v[152:155], v130 offset:2048
	v_mfma_f32_32x32x16_bf16 v[80:95], v[184:187], v[136:139], v[80:95]
	ds_read_b128 v[156:159], v130 offset:4096
	ds_read_b128 v[180:183], v130 offset:6144
	v_mfma_f32_32x32x16_bf16 v[64:79], v[188:191], v[136:139], v[64:79]
	s_add_u32 m0, s26, 0x22000
	s_nop 0
	global_load_lds_dwordx4 v[220:221], off
	v_lshl_add_u64 v[220:221], v[220:221], 0, s[6:7]
	v_mfma_f32_32x32x16_bf16 v[48:63], v[184:187], v[140:143], v[48:63]
	v_mfma_f32_32x32x16_bf16 v[32:47], v[188:191], v[140:143], v[32:47]
	v_mfma_f32_32x32x16_bf16 v[16:31], v[184:187], v[144:147], v[16:31]
	v_mfma_f32_32x32x16_bf16 v[0:15], v[188:191], v[144:147], v[0:15]
	s_add_u32 m0, s26, 0x26000
	s_nop 0
	global_load_lds_dwordx4 v[224:225], off
	v_lshl_add_u64 v[224:225], v[224:225], 0, s[6:7]
	s_waitcnt lgkmcnt(0)
	s_waitcnt vmcnt(12)
	s_barrier
	s_waitcnt lgkmcnt(0)
	v_mfma_f32_32x32x16_bf16 v[112:127], v[192:195], v[148:151], v[112:127]
	ds_read_b128 v[184:187], v131 offset:32768
	ds_read_b128 v[132:135], v128 offset:32768
	v_mfma_f32_32x32x16_bf16 v[96:111], v[208:211], v[148:151], v[96:111]
	ds_read_b128 v[188:191], v131 offset:34816
	ds_read_b128 v[136:139], v128 offset:34816
	v_mfma_f32_32x32x16_bf16 v[80:95], v[192:195], v[152:155], v[80:95]
	ds_read_b128 v[140:143], v128 offset:36864
	ds_read_b128 v[144:147], v128 offset:38912
	v_mfma_f32_32x32x16_bf16 v[64:79], v[208:211], v[152:155], v[64:79]
	s_add_u32 m0, s26, 0x0
	s_nop 0
	global_load_lds_dwordx4 v[218:219], off
	v_lshl_add_u64 v[218:219], v[218:219], 0, s[6:7]
	v_mfma_f32_32x32x16_bf16 v[48:63], v[192:195], v[156:159], v[48:63]
	v_mfma_f32_32x32x16_bf16 v[32:47], v[208:211], v[156:159], v[32:47]
	v_mfma_f32_32x32x16_bf16 v[16:31], v[192:195], v[180:183], v[16:31]
	v_mfma_f32_32x32x16_bf16 v[0:15], v[208:211], v[180:183], v[0:15]
	s_add_u32 m0, s26, 0x4000
	s_nop 0
	global_load_lds_dwordx4 v[222:223], off
	v_lshl_add_u64 v[222:223], v[222:223], 0, s[6:7]
	s_waitcnt lgkmcnt(0)
	v_mfma_f32_32x32x16_bf16 v[112:127], v[184:187], v[132:135], v[112:127]
	ds_read_b128 v[192:195], v205 offset:32768
	ds_read_b128 v[148:151], v130 offset:32768
	v_mfma_f32_32x32x16_bf16 v[96:111], v[188:191], v[132:135], v[96:111]
	ds_read_b128 v[208:211], v205 offset:34816
	ds_read_b128 v[152:155], v130 offset:34816
	v_mfma_f32_32x32x16_bf16 v[80:95], v[184:187], v[136:139], v[80:95]
	ds_read_b128 v[156:159], v130 offset:36864
	ds_read_b128 v[180:183], v130 offset:38912
	v_mfma_f32_32x32x16_bf16 v[64:79], v[188:191], v[136:139], v[64:79]
	s_add_u32 m0, s26, 0x2000
	s_nop 0
	global_load_lds_dwordx4 v[220:221], off
	v_lshl_add_u64 v[220:221], v[220:221], 0, s[6:7]
	v_mfma_f32_32x32x16_bf16 v[48:63], v[184:187], v[140:143], v[48:63]
	v_mfma_f32_32x32x16_bf16 v[32:47], v[188:191], v[140:143], v[32:47]
	v_mfma_f32_32x32x16_bf16 v[16:31], v[184:187], v[144:147], v[16:31]
	v_mfma_f32_32x32x16_bf16 v[0:15], v[188:191], v[144:147], v[0:15]
	s_add_u32 m0, s26, 0x6000
	s_nop 0
	global_load_lds_dwordx4 v[224:225], off
	v_lshl_add_u64 v[224:225], v[224:225], 0, s[6:7]
	s_waitcnt lgkmcnt(0)
	s_waitcnt vmcnt(12)
	s_barrier
	s_waitcnt lgkmcnt(0)
	v_mfma_f32_32x32x16_bf16 v[112:127], v[192:195], v[148:151], v[112:127]
	ds_read_b128 v[184:187], v212
	ds_read_b128 v[132:135], v206
	v_mfma_f32_32x32x16_bf16 v[96:111], v[208:211], v[148:151], v[96:111]
	ds_read_b128 v[188:191], v212 offset:2048
	ds_read_b128 v[136:139], v206 offset:2048
	v_mfma_f32_32x32x16_bf16 v[80:95], v[192:195], v[152:155], v[80:95]
	ds_read_b128 v[140:143], v206 offset:4096
	ds_read_b128 v[144:147], v206 offset:6144
	v_mfma_f32_32x32x16_bf16 v[64:79], v[208:211], v[152:155], v[64:79]
	s_add_u32 m0, s26, 0x8000
	s_nop 0
	global_load_lds_dwordx4 v[218:219], off
	v_lshl_add_u64 v[218:219], v[218:219], 0, s[6:7]
	v_mfma_f32_32x32x16_bf16 v[48:63], v[192:195], v[156:159], v[48:63]
	v_mfma_f32_32x32x16_bf16 v[32:47], v[208:211], v[156:159], v[32:47]
	v_mfma_f32_32x32x16_bf16 v[16:31], v[192:195], v[180:183], v[16:31]
	v_mfma_f32_32x32x16_bf16 v[0:15], v[208:211], v[180:183], v[0:15]
	s_add_u32 m0, s26, 0xc000
	s_nop 0
	global_load_lds_dwordx4 v[222:223], off
	v_lshl_add_u64 v[222:223], v[222:223], 0, s[6:7]
	s_waitcnt lgkmcnt(0)
	v_mfma_f32_32x32x16_bf16 v[112:127], v[184:187], v[132:135], v[112:127]
	ds_read_b128 v[192:195], v213
	ds_read_b128 v[148:151], v207
	v_mfma_f32_32x32x16_bf16 v[96:111], v[188:191], v[132:135], v[96:111]
	ds_read_b128 v[208:211], v213 offset:2048
	ds_read_b128 v[152:155], v207 offset:2048
	v_mfma_f32_32x32x16_bf16 v[80:95], v[184:187], v[136:139], v[80:95]
	ds_read_b128 v[156:159], v207 offset:4096
	ds_read_b128 v[180:183], v207 offset:6144
	v_mfma_f32_32x32x16_bf16 v[64:79], v[188:191], v[136:139], v[64:79]
	s_add_u32 m0, s26, 0xa000
	s_nop 0
	global_load_lds_dwordx4 v[220:221], off
	v_lshl_add_u64 v[220:221], v[220:221], 0, s[6:7]
	v_mfma_f32_32x32x16_bf16 v[48:63], v[184:187], v[140:143], v[48:63]
	v_mfma_f32_32x32x16_bf16 v[32:47], v[188:191], v[140:143], v[32:47]
	v_mfma_f32_32x32x16_bf16 v[16:31], v[184:187], v[144:147], v[16:31]
	v_mfma_f32_32x32x16_bf16 v[0:15], v[188:191], v[144:147], v[0:15]
	s_add_u32 m0, s26, 0xe000
	s_nop 0
	global_load_lds_dwordx4 v[224:225], off
	v_lshl_add_u64 v[224:225], v[224:225], 0, s[6:7]
	s_waitcnt lgkmcnt(0)
	s_waitcnt vmcnt(12)
	s_barrier
; template <class AL, class BL, class EP>
; DI void gemm_tile256(AL al, BL bl, EP ep, int K, char* smem) {
;     ...
;   for (int kt = 0; kt < KT; kt += 2) {
;     G_STEP(0, kt);
;     if (kt + 1 >= KT) break;
;     G_STEP(1, kt + 1);
;   }
	s_waitcnt lgkmcnt(0)
	v_mfma_f32_32x32x16_bf16 v[112:127], v[192:195], v[148:151], v[112:127]
	ds_read_b128 v[184:187], v212 offset:32768
	ds_read_b128 v[132:135], v206 offset:32768
	v_mfma_f32_32x32x16_bf16 v[96:111], v[208:211], v[148:151], v[96:111]
	ds_read_b128 v[188:191], v212 offset:34816
	ds_read_b128 v[136:139], v206 offset:34816
	v_mfma_f32_32x32x16_bf16 v[80:95], v[192:195], v[152:155], v[80:95]
	ds_read_b128 v[140:143], v206 offset:36864
	ds_read_b128 v[144:147], v206 offset:38912
	v_mfma_f32_32x32x16_bf16 v[64:79], v[208:211], v[152:155], v[64:79]
	s_add_u32 m0, s26, 0x10000
	s_nop 0
	global_load_lds_dwordx4 v[218:219], off
	v_lshl_add_u64 v[218:219], v[218:219], 0, s[6:7]
	v_mfma_f32_32x32x16_bf16 v[48:63], v[192:195], v[156:159], v[48:63]
	v_mfma_f32_32x32x16_bf16 v[32:47], v[208:211], v[156:159], v[32:47]
	v_mfma_f32_32x32x16_bf16 v[16:31], v[192:195], v[180:183], v[16:31]
	v_mfma_f32_32x32x16_bf16 v[0:15], v[208:211], v[180:183], v[0:15]
	s_add_u32 m0, s26, 0x14000
	s_nop 0
	global_load_lds_dwordx4 v[222:223], off
	v_lshl_add_u64 v[222:223], v[222:223], 0, s[6:7]
	s_waitcnt lgkmcnt(0)
	v_mfma_f32_32x32x16_bf16 v[112:127], v[184:187], v[132:135], v[112:127]
	ds_read_b128 v[192:195], v213 offset:32768
	ds_read_b128 v[148:151], v207 offset:32768
	v_mfma_f32_32x32x16_bf16 v[96:111], v[188:191], v[132:135], v[96:111]
	ds_read_b128 v[208:211], v213 offset:34816
	ds_read_b128 v[152:155], v207 offset:34816
	v_mfma_f32_32x32x16_bf16 v[80:95], v[184:187], v[136:139], v[80:95]
	ds_read_b128 v[156:159], v207 offset:36864
	ds_read_b128 v[180:183], v207 offset:38912
	v_mfma_f32_32x32x16_bf16 v[64:79], v[188:191], v[136:139], v[64:79]
	s_add_u32 m0, s26, 0x12000
	s_nop 0
	global_load_lds_dwordx4 v[220:221], off
	v_lshl_add_u64 v[220:221], v[220:221], 0, s[6:7]
	v_mfma_f32_32x32x16_bf16 v[48:63], v[184:187], v[140:143], v[48:63]
	v_mfma_f32_32x32x16_bf16 v[32:47], v[188:191], v[140:143], v[32:47]
	v_mfma_f32_32x32x16_bf16 v[16:31], v[184:187], v[144:147], v[16:31]
	v_mfma_f32_32x32x16_bf16 v[0:15], v[188:191], v[144:147], v[0:15]
	s_add_u32 m0, s26, 0x16000
	s_nop 0
	global_load_lds_dwordx4 v[224:225], off
	v_lshl_add_u64 v[224:225], v[224:225], 0, s[6:7]
	s_waitcnt lgkmcnt(0)
	s_waitcnt vmcnt(12)
	s_barrier
	s_waitcnt lgkmcnt(0)
	v_mfma_f32_32x32x16_bf16 v[112:127], v[192:195], v[148:151], v[112:127]
	ds_read_b128 v[184:187], v216
	ds_read_b128 v[132:135], v214
	v_mfma_f32_32x32x16_bf16 v[96:111], v[208:211], v[148:151], v[96:111]
	ds_read_b128 v[188:191], v216 offset:2048
	ds_read_b128 v[136:139], v214 offset:2048
	v_mfma_f32_32x32x16_bf16 v[80:95], v[192:195], v[152:155], v[80:95]
	ds_read_b128 v[140:143], v214 offset:4096
	ds_read_b128 v[144:147], v214 offset:6144
	v_mfma_f32_32x32x16_bf16 v[64:79], v[208:211], v[152:155], v[64:79]
	v_mfma_f32_32x32x16_bf16 v[48:63], v[192:195], v[156:159], v[48:63]
	v_mfma_f32_32x32x16_bf16 v[32:47], v[208:211], v[156:159], v[32:47]
	v_mfma_f32_32x32x16_bf16 v[16:31], v[192:195], v[180:183], v[16:31]
	v_mfma_f32_32x32x16_bf16 v[0:15], v[208:211], v[180:183], v[0:15]
	s_waitcnt lgkmcnt(0)
	v_mfma_f32_32x32x16_bf16 v[112:127], v[184:187], v[132:135], v[112:127]
	ds_read_b128 v[192:195], v217
	ds_read_b128 v[148:151], v215
	v_mfma_f32_32x32x16_bf16 v[96:111], v[188:191], v[132:135], v[96:111]
	ds_read_b128 v[208:211], v217 offset:2048
	ds_read_b128 v[152:155], v215 offset:2048
	v_mfma_f32_32x32x16_bf16 v[80:95], v[184:187], v[136:139], v[80:95]
	ds_read_b128 v[156:159], v215 offset:4096
	ds_read_b128 v[180:183], v215 offset:6144
	v_mfma_f32_32x32x16_bf16 v[64:79], v[188:191], v[136:139], v[64:79]
	v_mfma_f32_32x32x16_bf16 v[48:63], v[184:187], v[140:143], v[48:63]
	v_mfma_f32_32x32x16_bf16 v[32:47], v[188:191], v[140:143], v[32:47]
	v_mfma_f32_32x32x16_bf16 v[16:31], v[184:187], v[144:147], v[16:31]
	v_mfma_f32_32x32x16_bf16 v[0:15], v[188:191], v[144:147], v[0:15]
	s_waitcnt lgkmcnt(0)
	s_waitcnt vmcnt(8)
	s_barrier
	s_waitcnt lgkmcnt(0)
	v_mfma_f32_32x32x16_bf16 v[112:127], v[192:195], v[148:151], v[112:127]
	ds_read_b128 v[184:187], v131
	ds_read_b128 v[132:135], v128
	v_mfma_f32_32x32x16_bf16 v[96:111], v[208:211], v[148:151], v[96:111]
	ds_read_b128 v[188:191], v131 offset:2048
	ds_read_b128 v[136:139], v128 offset:2048
	v_mfma_f32_32x32x16_bf16 v[80:95], v[192:195], v[152:155], v[80:95]
	ds_read_b128 v[140:143], v128 offset:4096
	ds_read_b128 v[144:147], v128 offset:6144
	v_mfma_f32_32x32x16_bf16 v[64:79], v[208:211], v[152:155], v[64:79]
	v_mfma_f32_32x32x16_bf16 v[48:63], v[192:195], v[156:159], v[48:63]
	v_mfma_f32_32x32x16_bf16 v[32:47], v[208:211], v[156:159], v[32:47]
	v_mfma_f32_32x32x16_bf16 v[16:31], v[192:195], v[180:183], v[16:31]
	v_mfma_f32_32x32x16_bf16 v[0:15], v[208:211], v[180:183], v[0:15]
	s_waitcnt lgkmcnt(0)
	v_mfma_f32_32x32x16_bf16 v[112:127], v[184:187], v[132:135], v[112:127]
	ds_read_b128 v[192:195], v205
	ds_read_b128 v[148:151], v130
	v_mfma_f32_32x32x16_bf16 v[96:111], v[188:191], v[132:135], v[96:111]
	ds_read_b128 v[208:211], v205 offset:2048
	ds_read_b128 v[152:155], v130 offset:2048
	v_mfma_f32_32x32x16_bf16 v[80:95], v[184:187], v[136:139], v[80:95]
	ds_read_b128 v[156:159], v130 offset:4096
	ds_read_b128 v[180:183], v130 offset:6144
	v_mfma_f32_32x32x16_bf16 v[64:79], v[188:191], v[136:139], v[64:79]
	v_mfma_f32_32x32x16_bf16 v[48:63], v[184:187], v[140:143], v[48:63]
	v_mfma_f32_32x32x16_bf16 v[32:47], v[188:191], v[140:143], v[32:47]
	v_mfma_f32_32x32x16_bf16 v[16:31], v[184:187], v[144:147], v[16:31]
	v_mfma_f32_32x32x16_bf16 v[0:15], v[188:191], v[144:147], v[0:15]
	s_waitcnt lgkmcnt(0)
	s_waitcnt vmcnt(4)
	s_barrier
; template <class AL, class BL, class EP>
; DI void gemm_tile256(AL al, BL bl, EP ep, int K, char* smem) {
;     ...
;   for (int kt = 0; kt < KT; kt += 2) {
;     G_STEP(0, kt);
;     if (kt + 1 >= KT) break;
;     G_STEP(1, kt + 1);
;   }
	s_waitcnt lgkmcnt(0)
	v_mfma_f32_32x32x16_bf16 v[112:127], v[192:195], v[148:151], v[112:127]
	ds_read_b128 v[184:187], v131 offset:32768
	ds_read_b128 v[132:135], v128 offset:32768
	v_mfma_f32_32x32x16_bf16 v[96:111], v[208:211], v[148:151], v[96:111]
	ds_read_b128 v[188:191], v131 offset:34816
	ds_read_b128 v[136:139], v128 offset:34816
	v_mfma_f32_32x32x16_bf16 v[80:95], v[192:195], v[152:155], v[80:95]
	ds_read_b128 v[140:143], v128 offset:36864
	ds_read_b128 v[144:147], v128 offset:38912
	v_mfma_f32_32x32x16_bf16 v[64:79], v[208:211], v[152:155], v[64:79]
	v_mfma_f32_32x32x16_bf16 v[48:63], v[192:195], v[156:159], v[48:63]
	v_mfma_f32_32x32x16_bf16 v[32:47], v[208:211], v[156:159], v[32:47]
	v_mfma_f32_32x32x16_bf16 v[16:31], v[192:195], v[180:183], v[16:31]
	v_mfma_f32_32x32x16_bf16 v[0:15], v[208:211], v[180:183], v[0:15]
	s_waitcnt lgkmcnt(0)
	v_mfma_f32_32x32x16_bf16 v[112:127], v[184:187], v[132:135], v[112:127]
	ds_read_b128 v[192:195], v205 offset:32768
	ds_read_b128 v[148:151], v130 offset:32768
	v_mfma_f32_32x32x16_bf16 v[96:111], v[188:191], v[132:135], v[96:111]
	ds_read_b128 v[208:211], v205 offset:34816
	ds_read_b128 v[152:155], v130 offset:34816
	v_mfma_f32_32x32x16_bf16 v[80:95], v[184:187], v[136:139], v[80:95]
	ds_read_b128 v[156:159], v130 offset:36864
	ds_read_b128 v[180:183], v130 offset:38912
	v_mfma_f32_32x32x16_bf16 v[64:79], v[188:191], v[136:139], v[64:79]
	v_mfma_f32_32x32x16_bf16 v[48:63], v[184:187], v[140:143], v[48:63]
	v_mfma_f32_32x32x16_bf16 v[32:47], v[188:191], v[140:143], v[32:47]
	v_mfma_f32_32x32x16_bf16 v[16:31], v[184:187], v[144:147], v[16:31]
	v_mfma_f32_32x32x16_bf16 v[0:15], v[188:191], v[144:147], v[0:15]
	s_waitcnt lgkmcnt(0)
	s_waitcnt vmcnt(0)
	s_barrier
	s_waitcnt lgkmcnt(0)
	v_mfma_f32_32x32x16_bf16 v[112:127], v[192:195], v[148:151], v[112:127]
	ds_read_b128 v[184:187], v212
	ds_read_b128 v[132:135], v206
	v_mfma_f32_32x32x16_bf16 v[96:111], v[208:211], v[148:151], v[96:111]
	ds_read_b128 v[188:191], v212 offset:2048
	ds_read_b128 v[136:139], v206 offset:2048
	v_mfma_f32_32x32x16_bf16 v[80:95], v[192:195], v[152:155], v[80:95]
	ds_read_b128 v[140:143], v206 offset:4096
	ds_read_b128 v[144:147], v206 offset:6144
	v_mfma_f32_32x32x16_bf16 v[64:79], v[208:211], v[152:155], v[64:79]
	v_mfma_f32_32x32x16_bf16 v[48:63], v[192:195], v[156:159], v[48:63]
	v_mfma_f32_32x32x16_bf16 v[32:47], v[208:211], v[156:159], v[32:47]
	v_mfma_f32_32x32x16_bf16 v[16:31], v[192:195], v[180:183], v[16:31]
	v_mfma_f32_32x32x16_bf16 v[0:15], v[208:211], v[180:183], v[0:15]
	s_waitcnt lgkmcnt(0)
	v_mfma_f32_32x32x16_bf16 v[112:127], v[184:187], v[132:135], v[112:127]
	ds_read_b128 v[192:195], v213
	ds_read_b128 v[148:151], v207
	v_mfma_f32_32x32x16_bf16 v[96:111], v[188:191], v[132:135], v[96:111]
	ds_read_b128 v[208:211], v213 offset:2048
	ds_read_b128 v[152:155], v207 offset:2048
	v_mfma_f32_32x32x16_bf16 v[80:95], v[184:187], v[136:139], v[80:95]
	ds_read_b128 v[156:159], v207 offset:4096
	ds_read_b128 v[180:183], v207 offset:6144
	v_mfma_f32_32x32x16_bf16 v[64:79], v[188:191], v[136:139], v[64:79]
	v_mfma_f32_32x32x16_bf16 v[48:63], v[184:187], v[140:143], v[48:63]
	v_mfma_f32_32x32x16_bf16 v[32:47], v[188:191], v[140:143], v[32:47]
	v_mfma_f32_32x32x16_bf16 v[16:31], v[184:187], v[144:147], v[16:31]
	v_mfma_f32_32x32x16_bf16 v[0:15], v[188:191], v[144:147], v[0:15]
	s_waitcnt lgkmcnt(0)
	s_waitcnt lgkmcnt(0)
	v_mfma_f32_32x32x16_bf16 v[112:127], v[192:195], v[148:151], v[112:127]
	v_mfma_f32_32x32x16_bf16 v[96:111], v[208:211], v[148:151], v[96:111]
	v_mfma_f32_32x32x16_bf16 v[80:95], v[192:195], v[152:155], v[80:95]
	v_mfma_f32_32x32x16_bf16 v[64:79], v[208:211], v[152:155], v[64:79]
	v_mfma_f32_32x32x16_bf16 v[48:63], v[192:195], v[156:159], v[48:63]
	v_mfma_f32_32x32x16_bf16 v[32:47], v[208:211], v[156:159], v[32:47]
	v_mfma_f32_32x32x16_bf16 v[16:31], v[192:195], v[180:183], v[16:31]
	v_mfma_f32_32x32x16_bf16 v[0:15], v[208:211], v[180:183], v[0:15]
	s_nop 15
	s_nop 3
	s_branch .LBB0_1268
